# v21 + the same early issue of the leading half's epilogue loads (residual tile) in the four residual-add GEMM epilogues
# baseline (speedup 1.0000x reference)
; #define PG8_STAGE(bufoff, gbase, voff) do { _Pragma("unroll") for (int _i = 0; _i < 2; ++_i) \
;         __builtin_amdgcn_global_load_lds((const unsigned*)((const char*)(gbase) + (voff)[_i]), (PG8_LAS unsigned*)(lds + (bufoff) + ldsw + _i * 8192), 16, 0, 0); } while (0)
; #define PG8_LDA(dst, b, h) do { _Pragma("unroll") for (int m = 0; m < 4; ++m) _Pragma("unroll") for (int k = 0; k < 2; ++k) dst[m][k] = *(const PG8_LAS bf16x8*)(lds + PG8_SA(b, h) + aoff + m * 2048 + k * 1024); } while (0)
; #define PG8_LDB(dst, b, h) do { _Pragma("unroll") for (int n = 0; n < 2; ++n) _Pragma("unroll") for (int k = 0; k < 2; ++k) dst[n][k] = *(const PG8_LAS bf16x8*)(lds + PG8_SB(b, h) + boff + n * 2048 + k * 1024); } while (0)
; #define PG8_MMA(ai, bj, At, Bt) do { __builtin_amdgcn_s_setprio(1); _Pragma("unroll") for (int m = 0; m < 4; ++m) _Pragma("unroll") for (int n = 0; n < 2; ++n) _Pragma("unroll") for (int k = 0; k < 2; ++k) \
;         acc[ai][bj][m][n] = __builtin_amdgcn_mfma_f32_16x16x32_bf16(Bt[n][k], At[m][k], acc[ai][bj][m][n], 0, 0, 0); __builtin_amdgcn_s_setprio(0); } while (0)
; #define PG8_WAIT_V(n) asm volatile("s_waitcnt vmcnt(" #n ")" ::: "memory")
; #define PG8_WAIT_L(n) asm volatile("s_waitcnt lgkmcnt(" #n ")" ::: "memory")
; #define PG8_BAR __builtin_amdgcn_s_barrier()
; #define PG8_SCHED __builtin_amdgcn_sched_barrier(0)
; template <class Epi, class Sched, bool ALIGN_EPI = false, bool SP2 = false>
; __device__ __forceinline__ void gemm_phase(PG8_LAS unsigned char* lds, const Gemm g, const Sched& S, const Epi& E) {
;     ...
;             PG8_LDB(B0, 0, 0); PG8_LDB(B1, 0, 1); PG8_SCHED; PG8_LDA(At, 0, 0); PG8_STAGE(PG8_SA(1, 1), a1 + hstep, voffA);
;             PG8_WAIT_V(8); PG8_WAIT_L(0); PG8_BAR; PG8_MMA(0, 0, At, B0); PG8_MMA(0, 1, At, B1); PG8_BAR; PG8_SCHED;
;             PG8_LDA(At, 0, 1); PG8_STAGE(PG8_SB(0, 0), b2, voffB); PG8_STAGE(PG8_SB(0, 1), b2 + hstep, voffB); PG8_STAGE(PG8_SA(0, 0), a2, voffA);
;             PG8_WAIT_V(8); PG8_WAIT_L(0); PG8_BAR; PG8_MMA(1, 0, At, B0); PG8_MMA(1, 1, At, B1); PG8_BAR; PG8_SCHED;
.LBB0_1039:
	ds_read_b128 v[130:133], v241 offset:0
	ds_read_b128 v[134:137], v241 offset:1024
	ds_read_b128 v[138:141], v241 offset:2048
	ds_read_b128 v[142:145], v241 offset:3072
	ds_read_b128 v[146:149], v241 offset:16384
	ds_read_b128 v[150:153], v241 offset:17408
	ds_read_b128 v[172:175], v241 offset:18432
	ds_read_b128 v[176:179], v241 offset:19456
	s_add_u32 s24, s26, 0xfff00080
	s_addc_u32 s25, s27, -1
	s_cmp_eq_u32 s68, 60
	s_cselect_b32 s29, s15, s25
	s_cselect_b32 s28, s21, s24
	s_cselect_b32 s25, s13, s67
	s_cselect_b32 s24, s65, s66
	s_add_i32 m0, s23, 0xc000
	ds_read_b128 v[180:183], v185
	ds_read_b128 v[188:191], v185 offset:1024
	ds_read_b128 v[192:195], v185 offset:2048
	ds_read_b128 v[196:199], v185 offset:3072
	ds_read_b128 v[200:203], v185 offset:4096
	ds_read_b128 v[204:207], v185 offset:5120
	ds_read_b128 v[208:211], v185 offset:6144
	ds_read_b128 v[212:215], v185 offset:7168
	global_load_lds_dwordx4 v162, s[26:27]
	s_add_i32 m0, s23, 0xe000
	s_nop 0
	global_load_lds_dwordx4 v166, s[26:27]
	s_waitcnt vmcnt(8)
	s_waitcnt lgkmcnt(0)
	s_barrier
	s_waitcnt lgkmcnt(0)
	v_mfma_f32_16x16x32_bf16 v[114:117], v[130:133], v[180:183], v[114:117]
	v_mfma_f32_16x16x32_bf16 v[114:117], v[134:137], v[188:191], v[114:117]
	v_mfma_f32_16x16x32_bf16 v[106:109], v[134:137], v[196:199], v[106:109]
	v_mfma_f32_16x16x32_bf16 v[106:109], v[130:133], v[192:195], v[106:109]
	v_mfma_f32_16x16x32_bf16 v[90:93], v[130:133], v[200:203], v[90:93]
	v_mfma_f32_16x16x32_bf16 v[90:93], v[134:137], v[204:207], v[90:93]
	v_mfma_f32_16x16x32_bf16 v[74:77], v[134:137], v[212:215], v[74:77]
	v_mfma_f32_16x16x32_bf16 v[74:77], v[130:133], v[208:211], v[74:77]
	v_mfma_f32_16x16x32_bf16 v[66:69], v[138:141], v[208:211], v[66:69]
	v_mfma_f32_16x16x32_bf16 v[66:69], v[142:145], v[212:215], v[66:69]
	v_mfma_f32_16x16x32_bf16 v[82:85], v[142:145], v[204:207], v[82:85]
	v_mfma_f32_16x16x32_bf16 v[82:85], v[138:141], v[200:203], v[82:85]
	v_mfma_f32_16x16x32_bf16 v[98:101], v[138:141], v[192:195], v[98:101]
	v_mfma_f32_16x16x32_bf16 v[98:101], v[142:145], v[196:199], v[98:101]
	v_mfma_f32_16x16x32_bf16 v[118:121], v[142:145], v[188:191], v[118:121]
	v_mfma_f32_16x16x32_bf16 v[118:121], v[138:141], v[180:183], v[118:121]
	v_mfma_f32_16x16x32_bf16 v[122:125], v[146:149], v[180:183], v[122:125]
	v_mfma_f32_16x16x32_bf16 v[122:125], v[150:153], v[188:191], v[122:125]
	v_mfma_f32_16x16x32_bf16 v[110:113], v[150:153], v[196:199], v[110:113]
	v_mfma_f32_16x16x32_bf16 v[110:113], v[146:149], v[192:195], v[110:113]
	v_mfma_f32_16x16x32_bf16 v[94:97], v[146:149], v[200:203], v[94:97]
	v_mfma_f32_16x16x32_bf16 v[94:97], v[150:153], v[204:207], v[94:97]
	v_mfma_f32_16x16x32_bf16 v[78:81], v[150:153], v[212:215], v[78:81]
	v_mfma_f32_16x16x32_bf16 v[78:81], v[146:149], v[208:211], v[78:81]
	v_mfma_f32_16x16x32_bf16 v[70:73], v[172:175], v[208:211], v[70:73]
	v_mfma_f32_16x16x32_bf16 v[70:73], v[176:179], v[212:215], v[70:73]
	v_mfma_f32_16x16x32_bf16 v[86:89], v[176:179], v[204:207], v[86:89]
	v_mfma_f32_16x16x32_bf16 v[86:89], v[172:175], v[200:203], v[86:89]
	v_mfma_f32_16x16x32_bf16 v[102:105], v[172:175], v[192:195], v[102:105]
	v_mfma_f32_16x16x32_bf16 v[102:105], v[176:179], v[196:199], v[102:105]
	v_mfma_f32_16x16x32_bf16 v[126:129], v[176:179], v[188:191], v[126:129]
	v_mfma_f32_16x16x32_bf16 v[126:129], v[172:175], v[180:183], v[126:129]
	s_barrier
	s_add_i32 s33, s62, s36
	s_mov_b32 m0, s33
	ds_read_b128 v[180:183], v185 offset:16384
	ds_read_b128 v[188:191], v185 offset:17408
	ds_read_b128 v[192:195], v185 offset:18432
	ds_read_b128 v[196:199], v185 offset:19456
	ds_read_b128 v[200:203], v185 offset:20480
	ds_read_b128 v[204:207], v185 offset:21504
	ds_read_b128 v[208:211], v185 offset:22528
	ds_read_b128 v[212:215], v185 offset:23552
	global_load_lds_dwordx4 v156, s[24:25]
	s_add_i32 m0, s33, 0x2000
	s_add_u32 s72, s24, 0x100000
	s_addc_u32 s73, s25, 0
	s_add_i32 s33, s63, s36
	global_load_lds_dwordx4 v160, s[24:25]
	s_mov_b32 m0, s33
	s_add_u32 s100, s28, 0x80
	s_addc_u32 s101, s29, 0
	global_load_lds_dwordx4 v156, s[72:73]
	s_add_i32 m0, s33, 0x2000
	s_nop 0
	global_load_lds_dwordx4 v160, s[72:73]
	s_mov_b32 m0, s23
	s_nop 0
	global_load_lds_dwordx4 v154, s[28:29]
	s_mov_b32 m0, s37
	s_nop 0
	global_load_lds_dwordx4 v158, s[28:29]
	s_waitcnt vmcnt(8)
	s_waitcnt lgkmcnt(0)
	s_barrier
	s_waitcnt lgkmcnt(0)
	v_mfma_f32_16x16x32_bf16 v[58:61], v[130:133], v[180:183], v[58:61]
	v_mfma_f32_16x16x32_bf16 v[58:61], v[134:137], v[188:191], v[58:61]
	v_mfma_f32_16x16x32_bf16 v[42:45], v[134:137], v[196:199], v[42:45]
	v_mfma_f32_16x16x32_bf16 v[42:45], v[130:133], v[192:195], v[42:45]
	v_mfma_f32_16x16x32_bf16 v[26:29], v[130:133], v[200:203], v[26:29]
	v_mfma_f32_16x16x32_bf16 v[26:29], v[134:137], v[204:207], v[26:29]
	v_mfma_f32_16x16x32_bf16 v[6:9], v[134:137], v[212:215], v[6:9]
	v_mfma_f32_16x16x32_bf16 v[6:9], v[130:133], v[208:211], v[6:9]
	v_mfma_f32_16x16x32_bf16 v[2:5], v[138:141], v[208:211], v[2:5]
	v_mfma_f32_16x16x32_bf16 v[2:5], v[142:145], v[212:215], v[2:5]
	v_mfma_f32_16x16x32_bf16 v[18:21], v[142:145], v[204:207], v[18:21]
	v_mfma_f32_16x16x32_bf16 v[18:21], v[138:141], v[200:203], v[18:21]
	v_mfma_f32_16x16x32_bf16 v[34:37], v[138:141], v[192:195], v[34:37]
	v_mfma_f32_16x16x32_bf16 v[34:37], v[142:145], v[196:199], v[34:37]
	v_mfma_f32_16x16x32_bf16 v[54:57], v[142:145], v[188:191], v[54:57]
	v_mfma_f32_16x16x32_bf16 v[54:57], v[138:141], v[180:183], v[54:57]
	v_mfma_f32_16x16x32_bf16 v[62:65], v[146:149], v[180:183], v[62:65]
	v_mfma_f32_16x16x32_bf16 v[62:65], v[150:153], v[188:191], v[62:65]
	v_mfma_f32_16x16x32_bf16 v[46:49], v[150:153], v[196:199], v[46:49]
	v_mfma_f32_16x16x32_bf16 v[46:49], v[146:149], v[192:195], v[46:49]
	v_mfma_f32_16x16x32_bf16 v[30:33], v[146:149], v[200:203], v[30:33]
	v_mfma_f32_16x16x32_bf16 v[30:33], v[150:153], v[204:207], v[30:33]
	v_mfma_f32_16x16x32_bf16 v[10:13], v[150:153], v[212:215], v[10:13]
	v_mfma_f32_16x16x32_bf16 v[10:13], v[146:149], v[208:211], v[10:13]
	v_mfma_f32_16x16x32_bf16 v[14:17], v[172:175], v[208:211], v[14:17]
	v_mfma_f32_16x16x32_bf16 v[14:17], v[176:179], v[212:215], v[14:17]
	v_mfma_f32_16x16x32_bf16 v[22:25], v[176:179], v[204:207], v[22:25]
	v_mfma_f32_16x16x32_bf16 v[22:25], v[172:175], v[200:203], v[22:25]
	v_mfma_f32_16x16x32_bf16 v[38:41], v[172:175], v[192:195], v[38:41]
	v_mfma_f32_16x16x32_bf16 v[38:41], v[176:179], v[196:199], v[38:41]
	v_mfma_f32_16x16x32_bf16 v[50:53], v[176:179], v[188:191], v[50:53]
	v_mfma_f32_16x16x32_bf16 v[50:53], v[172:175], v[180:183], v[50:53]
	s_barrier
; #define PG8_STAGE(bufoff, gbase, voff) do { _Pragma("unroll") for (int _i = 0; _i < 2; ++_i) \
;         __builtin_amdgcn_global_load_lds((const unsigned*)((const char*)(gbase) + (voff)[_i]), (PG8_LAS unsigned*)(lds + (bufoff) + ldsw + _i * 8192), 16, 0, 0); } while (0)
; #define PG8_LDA(dst, b, h) do { _Pragma("unroll") for (int m = 0; m < 4; ++m) _Pragma("unroll") for (int k = 0; k < 2; ++k) dst[m][k] = *(const PG8_LAS bf16x8*)(lds + PG8_SA(b, h) + aoff + m * 2048 + k * 1024); } while (0)
; #define PG8_LDB(dst, b, h) do { _Pragma("unroll") for (int n = 0; n < 2; ++n) _Pragma("unroll") for (int k = 0; k < 2; ++k) dst[n][k] = *(const PG8_LAS bf16x8*)(lds + PG8_SB(b, h) + boff + n * 2048 + k * 1024); } while (0)
; #define PG8_MMA(ai, bj, At, Bt) do { __builtin_amdgcn_s_setprio(1); _Pragma("unroll") for (int m = 0; m < 4; ++m) _Pragma("unroll") for (int n = 0; n < 2; ++n) _Pragma("unroll") for (int k = 0; k < 2; ++k) \
;         acc[ai][bj][m][n] = __builtin_amdgcn_mfma_f32_16x16x32_bf16(Bt[n][k], At[m][k], acc[ai][bj][m][n], 0, 0, 0); __builtin_amdgcn_s_setprio(0); } while (0)
; #define PG8_WAIT_V(n) asm volatile("s_waitcnt vmcnt(" #n ")" ::: "memory")
; #define PG8_WAIT_L(n) asm volatile("s_waitcnt lgkmcnt(" #n ")" ::: "memory")
; #define PG8_BAR __builtin_amdgcn_s_barrier()
; #define PG8_SCHED __builtin_amdgcn_sched_barrier(0)
; template <class Epi, class Sched, bool ALIGN_EPI = false, bool SP2 = false>
; __device__ __forceinline__ void gemm_phase(PG8_LAS unsigned char* lds, const Gemm g, const Sched& S, const Epi& E) {
;     ...
;             PG8_LDB(B0, 1, 0); PG8_LDB(B1, 1, 1); PG8_SCHED; PG8_LDA(At, 1, 0); PG8_STAGE(PG8_SA(0, 1), a2 + hstep, voffA);
;             PG8_WAIT_V(8); PG8_WAIT_L(0); PG8_BAR; PG8_MMA(0, 0, At, B0); PG8_MMA(0, 1, At, B1); PG8_BAR; PG8_SCHED;
;             PG8_LDA(At, 1, 1); PG8_STAGE(PG8_SB(1, 0), b3, voffB); PG8_STAGE(PG8_SB(1, 1), b3 + hstep, voffB); PG8_STAGE(PG8_SA(1, 0), a3, voffA);
;             PG8_WAIT_V(8); PG8_WAIT_L(0); PG8_BAR; PG8_MMA(1, 0, At, B0); PG8_MMA(1, 1, At, B1); PG8_BAR; PG8_SCHED;
	s_add_i32 s33, 0, 0x18000
	s_add_i32 s42, 0, 0x1c000
	ds_read_b128 v[130:133], v241 offset:32768
	ds_read_b128 v[134:137], v241 offset:33792
	ds_read_b128 v[138:141], v241 offset:34816
	ds_read_b128 v[142:145], v241 offset:35840
	ds_read_b128 v[146:149], v241 offset:49152
	ds_read_b128 v[150:153], v241 offset:50176
	ds_read_b128 v[172:175], v241 offset:51200
	ds_read_b128 v[176:179], v241 offset:52224
	s_add_u32 s28, s28, 0x100000
	s_addc_u32 s29, s29, 0
	s_mov_b32 m0, s40
	ds_read_b128 v[180:183], v185 offset:32768
	ds_read_b128 v[188:191], v185 offset:33792
	ds_read_b128 v[192:195], v185 offset:34816
	ds_read_b128 v[196:199], v185 offset:35840
	ds_read_b128 v[200:203], v185 offset:36864
	ds_read_b128 v[204:207], v185 offset:37888
	ds_read_b128 v[208:211], v185 offset:38912
	ds_read_b128 v[212:215], v185 offset:39936
	global_load_lds_dwordx4 v154, s[28:29]
	s_mov_b32 m0, s41
	s_nop 0
	global_load_lds_dwordx4 v158, s[28:29]
	s_waitcnt vmcnt(8)
	s_waitcnt lgkmcnt(0)
	s_barrier
	s_waitcnt lgkmcnt(0)
	v_mfma_f32_16x16x32_bf16 v[114:117], v[130:133], v[180:183], v[114:117]
	v_mfma_f32_16x16x32_bf16 v[114:117], v[134:137], v[188:191], v[114:117]
	v_mfma_f32_16x16x32_bf16 v[106:109], v[134:137], v[196:199], v[106:109]
	v_mfma_f32_16x16x32_bf16 v[106:109], v[130:133], v[192:195], v[106:109]
	v_mfma_f32_16x16x32_bf16 v[90:93], v[130:133], v[200:203], v[90:93]
	v_mfma_f32_16x16x32_bf16 v[90:93], v[134:137], v[204:207], v[90:93]
	v_mfma_f32_16x16x32_bf16 v[74:77], v[134:137], v[212:215], v[74:77]
	v_mfma_f32_16x16x32_bf16 v[74:77], v[130:133], v[208:211], v[74:77]
	v_mfma_f32_16x16x32_bf16 v[66:69], v[138:141], v[208:211], v[66:69]
	v_mfma_f32_16x16x32_bf16 v[66:69], v[142:145], v[212:215], v[66:69]
	v_mfma_f32_16x16x32_bf16 v[82:85], v[142:145], v[204:207], v[82:85]
	v_mfma_f32_16x16x32_bf16 v[82:85], v[138:141], v[200:203], v[82:85]
	v_mfma_f32_16x16x32_bf16 v[98:101], v[138:141], v[192:195], v[98:101]
	v_mfma_f32_16x16x32_bf16 v[98:101], v[142:145], v[196:199], v[98:101]
	v_mfma_f32_16x16x32_bf16 v[118:121], v[142:145], v[188:191], v[118:121]
	v_mfma_f32_16x16x32_bf16 v[118:121], v[138:141], v[180:183], v[118:121]
	v_mfma_f32_16x16x32_bf16 v[122:125], v[146:149], v[180:183], v[122:125]
	v_mfma_f32_16x16x32_bf16 v[122:125], v[150:153], v[188:191], v[122:125]
	v_mfma_f32_16x16x32_bf16 v[110:113], v[150:153], v[196:199], v[110:113]
	v_mfma_f32_16x16x32_bf16 v[110:113], v[146:149], v[192:195], v[110:113]
	v_mfma_f32_16x16x32_bf16 v[94:97], v[146:149], v[200:203], v[94:97]
	v_mfma_f32_16x16x32_bf16 v[94:97], v[150:153], v[204:207], v[94:97]
	v_mfma_f32_16x16x32_bf16 v[78:81], v[150:153], v[212:215], v[78:81]
	v_mfma_f32_16x16x32_bf16 v[78:81], v[146:149], v[208:211], v[78:81]
	v_mfma_f32_16x16x32_bf16 v[70:73], v[172:175], v[208:211], v[70:73]
	v_mfma_f32_16x16x32_bf16 v[70:73], v[176:179], v[212:215], v[70:73]
	v_mfma_f32_16x16x32_bf16 v[86:89], v[176:179], v[204:207], v[86:89]
	v_mfma_f32_16x16x32_bf16 v[86:89], v[172:175], v[200:203], v[86:89]
	v_mfma_f32_16x16x32_bf16 v[102:105], v[172:175], v[192:195], v[102:105]
	v_mfma_f32_16x16x32_bf16 v[102:105], v[176:179], v[196:199], v[102:105]
	v_mfma_f32_16x16x32_bf16 v[126:129], v[176:179], v[188:191], v[126:129]
	v_mfma_f32_16x16x32_bf16 v[126:129], v[172:175], v[180:183], v[126:129]
	s_barrier
	s_add_i32 s28, s33, s36
	s_add_i32 m0, s28, 0xffffff80
	ds_read_b128 v[180:183], v185 offset:49152
	ds_read_b128 v[188:191], v185 offset:50176
	ds_read_b128 v[192:195], v185 offset:51200
	ds_read_b128 v[196:199], v185 offset:52224
	ds_read_b128 v[200:203], v185 offset:53248
	ds_read_b128 v[204:207], v185 offset:54272
	ds_read_b128 v[208:211], v185 offset:55296
	ds_read_b128 v[212:215], v185 offset:56320
	global_load_lds_dwordx4 v156, s[24:25] offset:128
	s_add_i32 m0, s28, 0x1f80
	s_add_i32 s28, s42, s36
	global_load_lds_dwordx4 v160, s[24:25] offset:128
	s_add_u32 s24, s24, 0x100080
	s_addc_u32 s25, s25, 0
	s_mov_b32 m0, s28
	s_nop 0
	global_load_lds_dwordx4 v156, s[24:25]
	s_add_i32 m0, s28, 0x2000
	s_nop 0
	global_load_lds_dwordx4 v160, s[24:25]
	s_mov_b32 m0, s46
	s_nop 0
	global_load_lds_dwordx4 v154, s[100:101]
	s_mov_b32 m0, s47
	s_nop 0
	global_load_lds_dwordx4 v158, s[100:101]
	s_waitcnt vmcnt(8)
	s_waitcnt lgkmcnt(0)
	s_barrier
; #define PG8_STAGE(bufoff, gbase, voff) do { _Pragma("unroll") for (int _i = 0; _i < 2; ++_i) \
;         __builtin_amdgcn_global_load_lds((const unsigned*)((const char*)(gbase) + (voff)[_i]), (PG8_LAS unsigned*)(lds + (bufoff) + ldsw + _i * 8192), 16, 0, 0); } while (0)
; #define PG8_LDA(dst, b, h) do { _Pragma("unroll") for (int m = 0; m < 4; ++m) _Pragma("unroll") for (int k = 0; k < 2; ++k) dst[m][k] = *(const PG8_LAS bf16x8*)(lds + PG8_SA(b, h) + aoff + m * 2048 + k * 1024); } while (0)
; #define PG8_MMA(ai, bj, At, Bt) do { __builtin_amdgcn_s_setprio(1); _Pragma("unroll") for (int m = 0; m < 4; ++m) _Pragma("unroll") for (int n = 0; n < 2; ++n) _Pragma("unroll") for (int k = 0; k < 2; ++k) \
;         acc[ai][bj][m][n] = __builtin_amdgcn_mfma_f32_16x16x32_bf16(Bt[n][k], At[m][k], acc[ai][bj][m][n], 0, 0, 0); __builtin_amdgcn_s_setprio(0); } while (0)
; #define PG8_WAIT_V(n) asm volatile("s_waitcnt vmcnt(" #n ")" ::: "memory")
; #define PG8_WAIT_L(n) asm volatile("s_waitcnt lgkmcnt(" #n ")" ::: "memory")
; #define PG8_BAR __builtin_amdgcn_s_barrier()
; #define PG8_SCHED __builtin_amdgcn_sched_barrier(0)
;     __device__ __forceinline__ void operator()(const f32x4 (&acc)[2][2][4][2], const Unit& u, int wr, int wc, int fr, int fq) const {
;     ...
;                 for (int bj = 0; bj < 2; ++bj) { const size_t off = (size_t)(row0 + ai * HALF + m * 16) * ldc + col0 + bj * HALF;
;                     if (BASE_F32) { const float* bp = (const float*)base + off; b0[m][bj] = *(const f32x4*)bp; b1[m][bj] = *(const f32x4*)(bp + 4); }
;                     else { const u32x4 r = *(const u32x4*)((const bf16_t*)base + off);
; template <class Epi, class Sched, bool ALIGN_EPI = false, bool SP2 = false>
; __device__ __forceinline__ void gemm_phase(PG8_LAS unsigned char* lds, const Gemm g, const Sched& S, const Epi& E) {
;     ...
;             PG8_WAIT_V(8); PG8_WAIT_L(0); PG8_BAR; PG8_MMA(0, 0, At, B0); PG8_MMA(0, 1, At, B1); PG8_BAR; PG8_SCHED;
;             PG8_LDA(At, 1, 1); PG8_STAGE(PG8_SB(1, 0), b3, voffB); PG8_STAGE(PG8_SB(1, 1), b3 + hstep, voffB); PG8_STAGE(PG8_SA(1, 0), a3, voffA);
;             PG8_WAIT_V(8); PG8_WAIT_L(0); PG8_BAR; PG8_MMA(1, 0, At, B0); PG8_MMA(1, 1, At, B1); PG8_BAR; PG8_SCHED;
	s_waitcnt lgkmcnt(0)
	v_mfma_f32_16x16x32_bf16 v[58:61], v[130:133], v[180:183], v[58:61]
	v_mfma_f32_16x16x32_bf16 v[58:61], v[134:137], v[188:191], v[58:61]
	v_mfma_f32_16x16x32_bf16 v[42:45], v[134:137], v[196:199], v[42:45]
	v_mfma_f32_16x16x32_bf16 v[42:45], v[130:133], v[192:195], v[42:45]
	v_mfma_f32_16x16x32_bf16 v[26:29], v[130:133], v[200:203], v[26:29]
	v_mfma_f32_16x16x32_bf16 v[26:29], v[134:137], v[204:207], v[26:29]
	v_mfma_f32_16x16x32_bf16 v[6:9], v[134:137], v[212:215], v[6:9]
	v_mfma_f32_16x16x32_bf16 v[6:9], v[130:133], v[208:211], v[6:9]
	v_mfma_f32_16x16x32_bf16 v[2:5], v[138:141], v[208:211], v[2:5]
	v_mfma_f32_16x16x32_bf16 v[2:5], v[142:145], v[212:215], v[2:5]
	v_mfma_f32_16x16x32_bf16 v[18:21], v[142:145], v[204:207], v[18:21]
	v_mfma_f32_16x16x32_bf16 v[18:21], v[138:141], v[200:203], v[18:21]
	v_mfma_f32_16x16x32_bf16 v[34:37], v[138:141], v[192:195], v[34:37]
	v_mfma_f32_16x16x32_bf16 v[34:37], v[142:145], v[196:199], v[34:37]
	v_mfma_f32_16x16x32_bf16 v[54:57], v[142:145], v[188:191], v[54:57]
	v_mfma_f32_16x16x32_bf16 v[54:57], v[138:141], v[180:183], v[54:57]
	v_mfma_f32_16x16x32_bf16 v[62:65], v[146:149], v[180:183], v[62:65]
	v_mfma_f32_16x16x32_bf16 v[62:65], v[150:153], v[188:191], v[62:65]
	v_mfma_f32_16x16x32_bf16 v[46:49], v[150:153], v[196:199], v[46:49]
	v_mfma_f32_16x16x32_bf16 v[46:49], v[146:149], v[192:195], v[46:49]
	v_mfma_f32_16x16x32_bf16 v[30:33], v[146:149], v[200:203], v[30:33]
	v_mfma_f32_16x16x32_bf16 v[30:33], v[150:153], v[204:207], v[30:33]
	v_mfma_f32_16x16x32_bf16 v[10:13], v[150:153], v[212:215], v[10:13]
	v_mfma_f32_16x16x32_bf16 v[10:13], v[146:149], v[208:211], v[10:13]
	v_mfma_f32_16x16x32_bf16 v[14:17], v[172:175], v[208:211], v[14:17]
	v_mfma_f32_16x16x32_bf16 v[14:17], v[176:179], v[212:215], v[14:17]
	v_mfma_f32_16x16x32_bf16 v[22:25], v[176:179], v[204:207], v[22:25]
	v_mfma_f32_16x16x32_bf16 v[22:25], v[172:175], v[200:203], v[22:25]
	v_mfma_f32_16x16x32_bf16 v[38:41], v[172:175], v[192:195], v[38:41]
	v_mfma_f32_16x16x32_bf16 v[38:41], v[176:179], v[196:199], v[38:41]
	v_mfma_f32_16x16x32_bf16 v[50:53], v[176:179], v[188:191], v[50:53]
	v_mfma_f32_16x16x32_bf16 v[50:53], v[172:175], v[180:183], v[50:53]
	s_barrier
	s_add_i32 s68, s68, 2
	s_add_u32 s26, s26, 0x100
	s_addc_u32 s27, s27, 0
	s_add_u32 s66, s66, 0x100
	s_addc_u32 s67, s67, 0
	s_cmp_gt_u32 s68, 61
	s_cbranch_scc0 .LBB0_1039
	s_and_b64 vcc, exec, s[10:11]
	s_cbranch_vccz .LBB0_1042
	v_lshl_or_b32 v172, s22, 8, v184
	v_lshl_add_u32 v176, s20, 8, v1
	v_ashrrev_i32_e32 v173, 31, v172
	v_lshlrev_b64 v[196:197], 1, v[172:173]
	v_ashrrev_i32_e32 v177, 31, v176
	v_lshl_add_u64 v[174:175], s[96:97], 0, v[196:197]
	v_lshlrev_b64 v[198:199], 13, v[176:177]
	v_lshl_add_u64 v[130:131], v[174:175], 0, v[198:199]
	global_load_dwordx4 v[188:191], v[130:131], off
	global_load_dwordx4 v[192:195], v[130:131], off offset:256
	v_or_b32_e32 v182, 16, v176
	v_or_b32_e32 v180, 32, v176
	v_or_b32_e32 v178, 48, v176
	v_ashrrev_i32_e32 v183, 31, v182
	v_ashrrev_i32_e32 v181, 31, v180
	v_ashrrev_i32_e32 v179, 31, v178
	v_lshlrev_b64 v[130:131], 13, v[182:183]
	v_lshlrev_b64 v[132:133], 13, v[180:181]
	v_lshlrev_b64 v[134:135], 13, v[178:179]
	v_lshl_add_u64 v[130:131], v[174:175], 0, v[130:131]
	v_lshl_add_u64 v[132:133], v[174:175], 0, v[132:133]
	v_lshl_add_u64 v[200:201], v[174:175], 0, v[134:135]
	global_load_dwordx4 v[150:153], v[130:131], off
	global_load_dwordx4 v[146:149], v[130:131], off offset:256
	global_load_dwordx4 v[142:145], v[132:133], off
	global_load_dwordx4 v[138:141], v[132:133], off offset:256
	global_load_dwordx4 v[134:137], v[200:201], off
	s_nop 0
	global_load_dwordx4 v[130:133], v[200:201], off offset:256
	s_barrier
	s_branch .Lepi_rest_1042

; __device__ __forceinline__ unsigned cvt_pk_bf16(float lo, float hi) { unsigned r; asm volatile("v_cvt_pk_bf16_f32 %0, %1, %2" : "=v"(r) : "v"(lo), "v"(hi)); return r; }
; __device__ __forceinline__ unsigned cvt_pk_bf16(float lo, float hi) { unsigned r; asm volatile("v_cvt_pk_bf16_f32 %0, %1, %2" : "=v"(r) : "v"(lo), "v"(hi)); return r; }
;     __device__ __forceinline__ void operator()(const f32x4 (&acc)[2][2][4][2], const Unit& u, int wr, int wc, int fr, int fq) const {
;     ...
;                     else { const u32x4 r = *(const u32x4*)((const bf16_t*)base + off);
;                         b0[m][bj] = (f32x4){__uint_as_float(r.x << 16), __uint_as_float(r.x & 0xffff0000u), __uint_as_float(r.y << 16), __uint_as_float(r.y & 0xffff0000u)};
;                         b1[m][bj] = (f32x4){__uint_as_float(r.z << 16), __uint_as_float(r.z & 0xffff0000u), __uint_as_float(r.w << 16), __uint_as_float(r.w & 0xffff0000u)}; } }
; #pragma unroll
;             for (int m = 0; m < 4; ++m) { const int row = row0 + ai * HALF + m * 16; const size_t off = (size_t)row * ldc + col0; f32x2 q2 = {0.f, 0.f};
; #pragma unroll
;                 for (int bj = 0; bj < 2; ++bj) { const f32x4 v0 = acc[ai][bj][m][0] + b0[m][bj], v1 = acc[ai][bj][m][1] + b1[m][bj];
;                     { const f32x2 e0 = {v0[0], v0[1]}, e1 = {v0[2], v0[3]}, e2 = {v1[0], v1[1]}, e3 = {v1[2], v1[3]}; q2 = e0 * e0 + q2; q2 = e1 * e1 + q2; q2 = e2 * e2 + q2; q2 = e3 * e3 + q2; }
;                     u32x4 w; w.x = cvt_pk_bf16(v0[0], v0[1]); w.y = cvt_pk_bf16(v0[2], v0[3]); w.z = cvt_pk_bf16(v1[0], v1[1]); w.w = cvt_pk_bf16(v1[2], v1[3]);
;                     *(u32x4*)(out + off + bj * HALF) = w; }
;                 float q = q2.x + q2.y; q += __shfl_xor(q, 16); q += __shfl_xor(q, 32);
;                 if (fq == 0) atomicAdd(ssq + row, (ssq_t)(q * SSQ_FIX + 0.5f)); }
.Lepi_rest_1042:
	v_and_b32_e32 v200, 64, v186
	v_xor_b32_e32 v187, 16, v186
	v_add_u32_e32 v200, 64, v200
	v_xor_b32_e32 v201, 32, v186
	v_cmp_lt_i32_e32 vcc, v187, v200
	v_lshl_add_u64 v[198:199], s[96:97], 0, v[198:199]
	v_lshl_add_u64 v[196:197], v[198:199], 0, v[196:197]
	v_cndmask_b32_e32 v187, v186, v187, vcc
	v_cmp_lt_i32_e32 vcc, v201, v200
	v_lshlrev_b32_e32 v187, 2, v187
	s_waitcnt vmcnt(0)
	v_lshlrev_b32_e32 v198, 16, v188
	v_and_b32_e32 v199, 0xffff0000, v188
	v_lshlrev_b32_e32 v188, 16, v189
	v_and_b32_e32 v189, 0xffff0000, v189
	v_cndmask_b32_e32 v206, v186, v201, vcc
	v_lshlrev_b32_e32 v200, 16, v190
	v_and_b32_e32 v201, 0xffff0000, v190
	v_lshlrev_b32_e32 v190, 16, v191
	v_and_b32_e32 v191, 0xffff0000, v191
	v_pk_add_f32 v[116:117], v[116:117], v[188:189]
	v_pk_add_f32 v[188:189], v[114:115], v[198:199]
	v_pk_add_f32 v[120:121], v[120:121], v[190:191]
	v_pk_mul_f32 v[190:191], v[116:117], v[116:117]
	v_pk_add_f32 v[118:119], v[118:119], v[200:201]
	v_cvt_pk_bf16_f32 v114, v188, v189
	v_cvt_pk_bf16_f32 v115, v116, v117
	v_pk_fma_f32 v[116:117], v[188:189], v[188:189], v[190:191]
	v_lshlrev_b32_e32 v202, 16, v192
	v_and_b32_e32 v203, 0xffff0000, v192
	v_pk_fma_f32 v[116:117], v[118:119], v[118:119], v[116:117]
	v_lshlrev_b32_e32 v192, 16, v193
	v_and_b32_e32 v193, 0xffff0000, v193
	v_pk_add_f32 v[122:123], v[122:123], v[202:203]
	v_pk_fma_f32 v[116:117], v[120:121], v[120:121], v[116:117]
	v_lshlrev_b32_e32 v204, 16, v194
	v_and_b32_e32 v205, 0xffff0000, v194
	v_pk_add_f32 v[124:125], v[124:125], v[192:193]
	v_pk_fma_f32 v[116:117], v[122:123], v[122:123], v[116:117]
	v_lshlrev_b32_e32 v194, 16, v195
	v_and_b32_e32 v195, 0xffff0000, v195
	v_pk_add_f32 v[126:127], v[126:127], v[204:205]
	v_pk_fma_f32 v[116:117], v[124:125], v[124:125], v[116:117]
	v_pk_add_f32 v[128:129], v[128:129], v[194:195]
	v_pk_fma_f32 v[116:117], v[126:127], v[126:127], v[116:117]
	s_nop 0
	v_pk_fma_f32 v[116:117], v[128:129], v[128:129], v[116:117]
	s_nop 0
	v_add_f32_e32 v188, v116, v117
	ds_bpermute_b32 v189, v187, v188
	v_cvt_pk_bf16_f32 v116, v118, v119
	v_cvt_pk_bf16_f32 v117, v120, v121
	global_store_dwordx4 v[196:197], v[114:117], off
	v_cvt_pk_bf16_f32 v118, v122, v123
	v_cvt_pk_bf16_f32 v119, v124, v125
	v_cvt_pk_bf16_f32 v120, v126, v127
	v_cvt_pk_bf16_f32 v121, v128, v129
	global_store_dwordx4 v[196:197], v[118:121], off offset:256
	s_waitcnt lgkmcnt(0)
	v_add_f32_e32 v115, v188, v189
	v_lshlrev_b32_e32 v114, 2, v206
	ds_bpermute_b32 v116, v114, v115
	s_and_saveexec_b64 s[20:21], s[0:1]
	s_cbranch_execz .LBB0_1044
	s_waitcnt lgkmcnt(0)
	v_add_f32_e32 v115, v115, v116
	v_fma_f32 v115, v115, s64, 0.5
	v_trunc_f32_e32 v115, v115
	v_mul_f32_e32 v116, 0x2f800000, v115
	v_floor_f32_e32 v117, v116
	v_fmac_f32_e32 v115, 0xcf800000, v117
	v_cvt_u32_f32_e32 v116, v115
	v_cvt_u32_f32_e32 v117, v117
	v_lshl_add_u64 v[118:119], v[176:177], 3, s[4:5]
	global_atomic_add_x2 v[118:119], v[116:117], off

; #define PG8_STAGE(bufoff, gbase, voff) do { _Pragma("unroll") for (int _i = 0; _i < 2; ++_i) \
;         __builtin_amdgcn_global_load_lds((const unsigned*)((const char*)(gbase) + (voff)[_i]), (PG8_LAS unsigned*)(lds + (bufoff) + ldsw + _i * 8192), 16, 0, 0); } while (0)
; #define PG8_LDA(dst, b, h) do { _Pragma("unroll") for (int m = 0; m < 4; ++m) _Pragma("unroll") for (int k = 0; k < 2; ++k) dst[m][k] = *(const PG8_LAS bf16x8*)(lds + PG8_SA(b, h) + aoff + m * 2048 + k * 1024); } while (0)
; #define PG8_LDB(dst, b, h) do { _Pragma("unroll") for (int n = 0; n < 2; ++n) _Pragma("unroll") for (int k = 0; k < 2; ++k) dst[n][k] = *(const PG8_LAS bf16x8*)(lds + PG8_SB(b, h) + boff + n * 2048 + k * 1024); } while (0)
; #define PG8_MMA(ai, bj, At, Bt) do { __builtin_amdgcn_s_setprio(1); _Pragma("unroll") for (int m = 0; m < 4; ++m) _Pragma("unroll") for (int n = 0; n < 2; ++n) _Pragma("unroll") for (int k = 0; k < 2; ++k) \
;         acc[ai][bj][m][n] = __builtin_amdgcn_mfma_f32_16x16x32_bf16(Bt[n][k], At[m][k], acc[ai][bj][m][n], 0, 0, 0); __builtin_amdgcn_s_setprio(0); } while (0)
; #define PG8_WAIT_V(n) asm volatile("s_waitcnt vmcnt(" #n ")" ::: "memory")
; #define PG8_WAIT_L(n) asm volatile("s_waitcnt lgkmcnt(" #n ")" ::: "memory")
; #define PG8_BAR __builtin_amdgcn_s_barrier()
; #define PG8_SCHED __builtin_amdgcn_sched_barrier(0)
; template <class Epi, class Sched, bool ALIGN_EPI = false, bool SP2 = false>
; __device__ __forceinline__ void gemm_phase(PG8_LAS unsigned char* lds, const Gemm g, const Sched& S, const Epi& E) {
;     ...
;             PG8_LDB(B0, 0, 0); PG8_LDB(B1, 0, 1); PG8_SCHED; PG8_LDA(At, 0, 0); PG8_STAGE(PG8_SA(1, 1), a1 + hstep, voffA);
;             PG8_WAIT_V(8); PG8_WAIT_L(0); PG8_BAR; PG8_MMA(0, 0, At, B0); PG8_MMA(0, 1, At, B1); PG8_BAR; PG8_SCHED;
;             PG8_LDA(At, 0, 1); PG8_STAGE(PG8_SB(0, 0), b2, voffB); PG8_STAGE(PG8_SB(0, 1), b2 + hstep, voffB); PG8_STAGE(PG8_SA(0, 0), a2, voffA);
;             PG8_WAIT_V(8); PG8_WAIT_L(0); PG8_BAR; PG8_MMA(1, 0, At, B0); PG8_MMA(1, 1, At, B1); PG8_BAR; PG8_SCHED;
.LBB0_1245:
	ds_read_b128 v[130:133], v241 offset:0
	ds_read_b128 v[134:137], v241 offset:1024
	ds_read_b128 v[138:141], v241 offset:2048
	ds_read_b128 v[142:145], v241 offset:3072
	ds_read_b128 v[146:149], v241 offset:16384
	ds_read_b128 v[150:153], v241 offset:17408
	ds_read_b128 v[172:175], v241 offset:18432
	ds_read_b128 v[176:179], v241 offset:19456
	s_add_u32 s16, s18, 0xffd50080
	s_addc_u32 s17, s19, -1
	s_cmpk_eq_i32 s64, 0xa8
	s_cselect_b32 s21, s5, s17
	s_cselect_b32 s20, s4, s16
	s_cselect_b32 s17, s15, s63
	s_cselect_b32 s16, s14, s62
	s_add_i32 m0, s25, 0xc000
	ds_read_b128 v[180:183], v185
	ds_read_b128 v[188:191], v185 offset:1024
	ds_read_b128 v[192:195], v185 offset:2048
	ds_read_b128 v[196:199], v185 offset:3072
	ds_read_b128 v[200:203], v185 offset:4096
	ds_read_b128 v[204:207], v185 offset:5120
	ds_read_b128 v[208:211], v185 offset:6144
	ds_read_b128 v[212:215], v185 offset:7168
	global_load_lds_dwordx4 v162, s[18:19]
	s_add_i32 m0, s25, 0xe000
	s_nop 0
	global_load_lds_dwordx4 v166, s[18:19]
	s_waitcnt vmcnt(8)
	s_waitcnt lgkmcnt(0)
	s_barrier
	s_waitcnt lgkmcnt(0)
	v_mfma_f32_16x16x32_bf16 v[114:117], v[130:133], v[180:183], v[114:117]
	v_mfma_f32_16x16x32_bf16 v[114:117], v[134:137], v[188:191], v[114:117]
	v_mfma_f32_16x16x32_bf16 v[106:109], v[134:137], v[196:199], v[106:109]
	v_mfma_f32_16x16x32_bf16 v[106:109], v[130:133], v[192:195], v[106:109]
	v_mfma_f32_16x16x32_bf16 v[90:93], v[130:133], v[200:203], v[90:93]
	v_mfma_f32_16x16x32_bf16 v[90:93], v[134:137], v[204:207], v[90:93]
	v_mfma_f32_16x16x32_bf16 v[74:77], v[134:137], v[212:215], v[74:77]
	v_mfma_f32_16x16x32_bf16 v[74:77], v[130:133], v[208:211], v[74:77]
	v_mfma_f32_16x16x32_bf16 v[66:69], v[138:141], v[208:211], v[66:69]
	v_mfma_f32_16x16x32_bf16 v[66:69], v[142:145], v[212:215], v[66:69]
	v_mfma_f32_16x16x32_bf16 v[82:85], v[142:145], v[204:207], v[82:85]
	v_mfma_f32_16x16x32_bf16 v[82:85], v[138:141], v[200:203], v[82:85]
	v_mfma_f32_16x16x32_bf16 v[98:101], v[138:141], v[192:195], v[98:101]
	v_mfma_f32_16x16x32_bf16 v[98:101], v[142:145], v[196:199], v[98:101]
	v_mfma_f32_16x16x32_bf16 v[118:121], v[142:145], v[188:191], v[118:121]
	v_mfma_f32_16x16x32_bf16 v[118:121], v[138:141], v[180:183], v[118:121]
	v_mfma_f32_16x16x32_bf16 v[122:125], v[146:149], v[180:183], v[122:125]
	v_mfma_f32_16x16x32_bf16 v[122:125], v[150:153], v[188:191], v[122:125]
	v_mfma_f32_16x16x32_bf16 v[110:113], v[150:153], v[196:199], v[110:113]
	v_mfma_f32_16x16x32_bf16 v[110:113], v[146:149], v[192:195], v[110:113]
	v_mfma_f32_16x16x32_bf16 v[94:97], v[146:149], v[200:203], v[94:97]
	v_mfma_f32_16x16x32_bf16 v[94:97], v[150:153], v[204:207], v[94:97]
	v_mfma_f32_16x16x32_bf16 v[78:81], v[150:153], v[212:215], v[78:81]
	v_mfma_f32_16x16x32_bf16 v[78:81], v[146:149], v[208:211], v[78:81]
	v_mfma_f32_16x16x32_bf16 v[70:73], v[172:175], v[208:211], v[70:73]
	v_mfma_f32_16x16x32_bf16 v[70:73], v[176:179], v[212:215], v[70:73]
	v_mfma_f32_16x16x32_bf16 v[86:89], v[176:179], v[204:207], v[86:89]
	v_mfma_f32_16x16x32_bf16 v[86:89], v[172:175], v[200:203], v[86:89]
	v_mfma_f32_16x16x32_bf16 v[102:105], v[172:175], v[192:195], v[102:105]
	v_mfma_f32_16x16x32_bf16 v[102:105], v[176:179], v[196:199], v[102:105]
	v_mfma_f32_16x16x32_bf16 v[126:129], v[176:179], v[188:191], v[126:129]
	v_mfma_f32_16x16x32_bf16 v[126:129], v[172:175], v[180:183], v[126:129]
	s_barrier
	s_add_i32 s33, s40, s24
	s_mov_b32 m0, s33
	ds_read_b128 v[180:183], v185 offset:16384
	ds_read_b128 v[188:191], v185 offset:17408
	ds_read_b128 v[192:195], v185 offset:18432
	ds_read_b128 v[196:199], v185 offset:19456
	ds_read_b128 v[200:203], v185 offset:20480
	ds_read_b128 v[204:207], v185 offset:21504
	ds_read_b128 v[208:211], v185 offset:22528
	ds_read_b128 v[212:215], v185 offset:23552
	global_load_lds_dwordx4 v156, s[16:17]
	s_add_i32 m0, s33, 0x2000
	s_add_u32 s66, s16, 0x2b0000
	s_addc_u32 s67, s17, 0
	s_add_i32 s33, s41, s24
	global_load_lds_dwordx4 v160, s[16:17]
	s_mov_b32 m0, s33
	s_add_u32 s100, s20, 0x80
	s_addc_u32 s101, s21, 0
	global_load_lds_dwordx4 v156, s[66:67]
	s_add_i32 m0, s33, 0x2000
	s_nop 0
	global_load_lds_dwordx4 v160, s[66:67]
	s_mov_b32 m0, s25
	s_nop 0
	global_load_lds_dwordx4 v154, s[20:21]
	s_mov_b32 m0, s26
	s_nop 0
	global_load_lds_dwordx4 v158, s[20:21]
	s_waitcnt vmcnt(8)
	s_waitcnt lgkmcnt(0)
	s_barrier
	s_waitcnt lgkmcnt(0)
	v_mfma_f32_16x16x32_bf16 v[58:61], v[130:133], v[180:183], v[58:61]
	v_mfma_f32_16x16x32_bf16 v[58:61], v[134:137], v[188:191], v[58:61]
	v_mfma_f32_16x16x32_bf16 v[42:45], v[134:137], v[196:199], v[42:45]
	v_mfma_f32_16x16x32_bf16 v[42:45], v[130:133], v[192:195], v[42:45]
	v_mfma_f32_16x16x32_bf16 v[26:29], v[130:133], v[200:203], v[26:29]
	v_mfma_f32_16x16x32_bf16 v[26:29], v[134:137], v[204:207], v[26:29]
	v_mfma_f32_16x16x32_bf16 v[6:9], v[134:137], v[212:215], v[6:9]
	v_mfma_f32_16x16x32_bf16 v[6:9], v[130:133], v[208:211], v[6:9]
	v_mfma_f32_16x16x32_bf16 v[2:5], v[138:141], v[208:211], v[2:5]
	v_mfma_f32_16x16x32_bf16 v[2:5], v[142:145], v[212:215], v[2:5]
	v_mfma_f32_16x16x32_bf16 v[18:21], v[142:145], v[204:207], v[18:21]
	v_mfma_f32_16x16x32_bf16 v[18:21], v[138:141], v[200:203], v[18:21]
	v_mfma_f32_16x16x32_bf16 v[34:37], v[138:141], v[192:195], v[34:37]
	v_mfma_f32_16x16x32_bf16 v[34:37], v[142:145], v[196:199], v[34:37]
	v_mfma_f32_16x16x32_bf16 v[54:57], v[142:145], v[188:191], v[54:57]
	v_mfma_f32_16x16x32_bf16 v[54:57], v[138:141], v[180:183], v[54:57]
	v_mfma_f32_16x16x32_bf16 v[62:65], v[146:149], v[180:183], v[62:65]
	v_mfma_f32_16x16x32_bf16 v[62:65], v[150:153], v[188:191], v[62:65]
	v_mfma_f32_16x16x32_bf16 v[46:49], v[150:153], v[196:199], v[46:49]
	v_mfma_f32_16x16x32_bf16 v[46:49], v[146:149], v[192:195], v[46:49]
	v_mfma_f32_16x16x32_bf16 v[30:33], v[146:149], v[200:203], v[30:33]
	v_mfma_f32_16x16x32_bf16 v[30:33], v[150:153], v[204:207], v[30:33]
	v_mfma_f32_16x16x32_bf16 v[10:13], v[150:153], v[212:215], v[10:13]
	v_mfma_f32_16x16x32_bf16 v[10:13], v[146:149], v[208:211], v[10:13]
	v_mfma_f32_16x16x32_bf16 v[14:17], v[172:175], v[208:211], v[14:17]
	v_mfma_f32_16x16x32_bf16 v[14:17], v[176:179], v[212:215], v[14:17]
	v_mfma_f32_16x16x32_bf16 v[22:25], v[176:179], v[204:207], v[22:25]
	v_mfma_f32_16x16x32_bf16 v[22:25], v[172:175], v[200:203], v[22:25]
	v_mfma_f32_16x16x32_bf16 v[38:41], v[172:175], v[192:195], v[38:41]
	v_mfma_f32_16x16x32_bf16 v[38:41], v[176:179], v[196:199], v[38:41]
	v_mfma_f32_16x16x32_bf16 v[50:53], v[176:179], v[188:191], v[50:53]
	v_mfma_f32_16x16x32_bf16 v[50:53], v[172:175], v[180:183], v[50:53]
	s_barrier
; #define PG8_STAGE(bufoff, gbase, voff) do { _Pragma("unroll") for (int _i = 0; _i < 2; ++_i) \
;         __builtin_amdgcn_global_load_lds((const unsigned*)((const char*)(gbase) + (voff)[_i]), (PG8_LAS unsigned*)(lds + (bufoff) + ldsw + _i * 8192), 16, 0, 0); } while (0)
; #define PG8_LDA(dst, b, h) do { _Pragma("unroll") for (int m = 0; m < 4; ++m) _Pragma("unroll") for (int k = 0; k < 2; ++k) dst[m][k] = *(const PG8_LAS bf16x8*)(lds + PG8_SA(b, h) + aoff + m * 2048 + k * 1024); } while (0)
; #define PG8_LDB(dst, b, h) do { _Pragma("unroll") for (int n = 0; n < 2; ++n) _Pragma("unroll") for (int k = 0; k < 2; ++k) dst[n][k] = *(const PG8_LAS bf16x8*)(lds + PG8_SB(b, h) + boff + n * 2048 + k * 1024); } while (0)
; #define PG8_MMA(ai, bj, At, Bt) do { __builtin_amdgcn_s_setprio(1); _Pragma("unroll") for (int m = 0; m < 4; ++m) _Pragma("unroll") for (int n = 0; n < 2; ++n) _Pragma("unroll") for (int k = 0; k < 2; ++k) \
;         acc[ai][bj][m][n] = __builtin_amdgcn_mfma_f32_16x16x32_bf16(Bt[n][k], At[m][k], acc[ai][bj][m][n], 0, 0, 0); __builtin_amdgcn_s_setprio(0); } while (0)
; #define PG8_WAIT_V(n) asm volatile("s_waitcnt vmcnt(" #n ")" ::: "memory")
; #define PG8_WAIT_L(n) asm volatile("s_waitcnt lgkmcnt(" #n ")" ::: "memory")
; #define PG8_BAR __builtin_amdgcn_s_barrier()
; #define PG8_SCHED __builtin_amdgcn_sched_barrier(0)
; template <class Epi, class Sched, bool ALIGN_EPI = false, bool SP2 = false>
; __device__ __forceinline__ void gemm_phase(PG8_LAS unsigned char* lds, const Gemm g, const Sched& S, const Epi& E) {
;     ...
;             PG8_LDB(B0, 1, 0); PG8_LDB(B1, 1, 1); PG8_SCHED; PG8_LDA(At, 1, 0); PG8_STAGE(PG8_SA(0, 1), a2 + hstep, voffA);
;             PG8_WAIT_V(8); PG8_WAIT_L(0); PG8_BAR; PG8_MMA(0, 0, At, B0); PG8_MMA(0, 1, At, B1); PG8_BAR; PG8_SCHED;
;             PG8_LDA(At, 1, 1); PG8_STAGE(PG8_SB(1, 0), b3, voffB); PG8_STAGE(PG8_SB(1, 1), b3 + hstep, voffB); PG8_STAGE(PG8_SA(1, 0), a3, voffA);
;             PG8_WAIT_V(8); PG8_WAIT_L(0); PG8_BAR; PG8_MMA(1, 0, At, B0); PG8_MMA(1, 1, At, B1); PG8_BAR; PG8_SCHED;
	s_add_i32 s33, 0, 0x18000
	s_add_i32 s42, 0, 0x1c000
	ds_read_b128 v[130:133], v241 offset:32768
	ds_read_b128 v[134:137], v241 offset:33792
	ds_read_b128 v[138:141], v241 offset:34816
	ds_read_b128 v[142:145], v241 offset:35840
	ds_read_b128 v[146:149], v241 offset:49152
	ds_read_b128 v[150:153], v241 offset:50176
	ds_read_b128 v[172:175], v241 offset:51200
	ds_read_b128 v[176:179], v241 offset:52224
	s_add_u32 s20, s20, 0x2b0000
	s_addc_u32 s21, s21, 0
	s_mov_b32 m0, s27
	ds_read_b128 v[180:183], v185 offset:32768
	ds_read_b128 v[188:191], v185 offset:33792
	ds_read_b128 v[192:195], v185 offset:34816
	ds_read_b128 v[196:199], v185 offset:35840
	ds_read_b128 v[200:203], v185 offset:36864
	ds_read_b128 v[204:207], v185 offset:37888
	ds_read_b128 v[208:211], v185 offset:38912
	ds_read_b128 v[212:215], v185 offset:39936
	global_load_lds_dwordx4 v154, s[20:21]
	s_mov_b32 m0, s28
	s_nop 0
	global_load_lds_dwordx4 v158, s[20:21]
	s_waitcnt vmcnt(8)
	s_waitcnt lgkmcnt(0)
	s_barrier
	s_waitcnt lgkmcnt(0)
	v_mfma_f32_16x16x32_bf16 v[114:117], v[130:133], v[180:183], v[114:117]
	v_mfma_f32_16x16x32_bf16 v[114:117], v[134:137], v[188:191], v[114:117]
	v_mfma_f32_16x16x32_bf16 v[106:109], v[134:137], v[196:199], v[106:109]
	v_mfma_f32_16x16x32_bf16 v[106:109], v[130:133], v[192:195], v[106:109]
	v_mfma_f32_16x16x32_bf16 v[90:93], v[130:133], v[200:203], v[90:93]
	v_mfma_f32_16x16x32_bf16 v[90:93], v[134:137], v[204:207], v[90:93]
	v_mfma_f32_16x16x32_bf16 v[74:77], v[134:137], v[212:215], v[74:77]
	v_mfma_f32_16x16x32_bf16 v[74:77], v[130:133], v[208:211], v[74:77]
	v_mfma_f32_16x16x32_bf16 v[66:69], v[138:141], v[208:211], v[66:69]
	v_mfma_f32_16x16x32_bf16 v[66:69], v[142:145], v[212:215], v[66:69]
	v_mfma_f32_16x16x32_bf16 v[82:85], v[142:145], v[204:207], v[82:85]
	v_mfma_f32_16x16x32_bf16 v[82:85], v[138:141], v[200:203], v[82:85]
	v_mfma_f32_16x16x32_bf16 v[98:101], v[138:141], v[192:195], v[98:101]
	v_mfma_f32_16x16x32_bf16 v[98:101], v[142:145], v[196:199], v[98:101]
	v_mfma_f32_16x16x32_bf16 v[118:121], v[142:145], v[188:191], v[118:121]
	v_mfma_f32_16x16x32_bf16 v[118:121], v[138:141], v[180:183], v[118:121]
	v_mfma_f32_16x16x32_bf16 v[122:125], v[146:149], v[180:183], v[122:125]
	v_mfma_f32_16x16x32_bf16 v[122:125], v[150:153], v[188:191], v[122:125]
	v_mfma_f32_16x16x32_bf16 v[110:113], v[150:153], v[196:199], v[110:113]
	v_mfma_f32_16x16x32_bf16 v[110:113], v[146:149], v[192:195], v[110:113]
	v_mfma_f32_16x16x32_bf16 v[94:97], v[146:149], v[200:203], v[94:97]
	v_mfma_f32_16x16x32_bf16 v[94:97], v[150:153], v[204:207], v[94:97]
	v_mfma_f32_16x16x32_bf16 v[78:81], v[150:153], v[212:215], v[78:81]
	v_mfma_f32_16x16x32_bf16 v[78:81], v[146:149], v[208:211], v[78:81]
	v_mfma_f32_16x16x32_bf16 v[70:73], v[172:175], v[208:211], v[70:73]
	v_mfma_f32_16x16x32_bf16 v[70:73], v[176:179], v[212:215], v[70:73]
	v_mfma_f32_16x16x32_bf16 v[86:89], v[176:179], v[204:207], v[86:89]
	v_mfma_f32_16x16x32_bf16 v[86:89], v[172:175], v[200:203], v[86:89]
	v_mfma_f32_16x16x32_bf16 v[102:105], v[172:175], v[192:195], v[102:105]
	v_mfma_f32_16x16x32_bf16 v[102:105], v[176:179], v[196:199], v[102:105]
	v_mfma_f32_16x16x32_bf16 v[126:129], v[176:179], v[188:191], v[126:129]
	v_mfma_f32_16x16x32_bf16 v[126:129], v[172:175], v[180:183], v[126:129]
	s_barrier
	s_add_i32 s20, s33, s24
	s_add_i32 m0, s20, 0xffffff80
	ds_read_b128 v[180:183], v185 offset:49152
	ds_read_b128 v[188:191], v185 offset:50176
	ds_read_b128 v[192:195], v185 offset:51200
	ds_read_b128 v[196:199], v185 offset:52224
	ds_read_b128 v[200:203], v185 offset:53248
	ds_read_b128 v[204:207], v185 offset:54272
	ds_read_b128 v[208:211], v185 offset:55296
	ds_read_b128 v[212:215], v185 offset:56320
	global_load_lds_dwordx4 v156, s[16:17] offset:128
	s_add_i32 m0, s20, 0x1f80
	s_add_i32 s20, s42, s24
	global_load_lds_dwordx4 v160, s[16:17] offset:128
	s_add_u32 s16, s16, 0x2b0080
	s_addc_u32 s17, s17, 0
	s_mov_b32 m0, s20
	s_nop 0
	global_load_lds_dwordx4 v156, s[16:17]
	s_add_i32 m0, s20, 0x2000
	s_nop 0
	global_load_lds_dwordx4 v160, s[16:17]
	s_mov_b32 m0, s34
	s_nop 0
	global_load_lds_dwordx4 v154, s[100:101]
	s_mov_b32 m0, s35
	s_nop 0
	global_load_lds_dwordx4 v158, s[100:101]
	s_waitcnt vmcnt(8)
	s_waitcnt lgkmcnt(0)
	s_barrier
; #define PG8_STAGE(bufoff, gbase, voff) do { _Pragma("unroll") for (int _i = 0; _i < 2; ++_i) \
;         __builtin_amdgcn_global_load_lds((const unsigned*)((const char*)(gbase) + (voff)[_i]), (PG8_LAS unsigned*)(lds + (bufoff) + ldsw + _i * 8192), 16, 0, 0); } while (0)
; #define PG8_LDA(dst, b, h) do { _Pragma("unroll") for (int m = 0; m < 4; ++m) _Pragma("unroll") for (int k = 0; k < 2; ++k) dst[m][k] = *(const PG8_LAS bf16x8*)(lds + PG8_SA(b, h) + aoff + m * 2048 + k * 1024); } while (0)
; #define PG8_MMA(ai, bj, At, Bt) do { __builtin_amdgcn_s_setprio(1); _Pragma("unroll") for (int m = 0; m < 4; ++m) _Pragma("unroll") for (int n = 0; n < 2; ++n) _Pragma("unroll") for (int k = 0; k < 2; ++k) \
;         acc[ai][bj][m][n] = __builtin_amdgcn_mfma_f32_16x16x32_bf16(Bt[n][k], At[m][k], acc[ai][bj][m][n], 0, 0, 0); __builtin_amdgcn_s_setprio(0); } while (0)
; #define PG8_WAIT_V(n) asm volatile("s_waitcnt vmcnt(" #n ")" ::: "memory")
;     __device__ __forceinline__ void operator()(const f32x4 (&acc)[2][2][4][2], const Unit& u, int wr, int wc, int fr, int fq) const {
;     ...
;                 for (int bj = 0; bj < 2; ++bj) { const size_t off = (size_t)(row0 + ai * HALF + m * 16) * ldc + col0 + bj * HALF;
;                     if (BASE_F32) { const float* bp = (const float*)base + off; b0[m][bj] = *(const f32x4*)bp; b1[m][bj] = *(const f32x4*)(bp + 4); }
;                     else { const u32x4 r = *(const u32x4*)((const bf16_t*)base + off);
;                         b0[m][bj] = (f32x4){__uint_as_float(r.x << 16), __uint_as_float(r.x & 0xffff0000u), __uint_as_float(r.y << 16), __uint_as_float(r.y & 0xffff0000u)};
;                         b1[m][bj] = (f32x4){__uint_as_float(r.z << 16), __uint_as_float(r.z & 0xffff0000u), __uint_as_float(r.w << 16), __uint_as_float(r.w & 0xffff0000u)}; } }
; template <class Epi, class Sched, bool ALIGN_EPI = false, bool SP2 = false>
; __device__ __forceinline__ void gemm_phase(PG8_LAS unsigned char* lds, const Gemm g, const Sched& S, const Epi& E) {
;     ...
;             PG8_WAIT_V(8); PG8_WAIT_L(0); PG8_BAR; PG8_MMA(0, 0, At, B0); PG8_MMA(0, 1, At, B1); PG8_BAR; PG8_SCHED;
;             PG8_LDA(At, 1, 1); PG8_STAGE(PG8_SB(1, 0), b3, voffB); PG8_STAGE(PG8_SB(1, 1), b3 + hstep, voffB); PG8_STAGE(PG8_SA(1, 0), a3, voffA);
;             PG8_WAIT_V(8); PG8_WAIT_L(0); PG8_BAR; PG8_MMA(1, 0, At, B0); PG8_MMA(1, 1, At, B1); PG8_BAR; PG8_SCHED;
	s_waitcnt lgkmcnt(0)
	v_mfma_f32_16x16x32_bf16 v[58:61], v[130:133], v[180:183], v[58:61]
	v_mfma_f32_16x16x32_bf16 v[58:61], v[134:137], v[188:191], v[58:61]
	v_mfma_f32_16x16x32_bf16 v[42:45], v[134:137], v[196:199], v[42:45]
	v_mfma_f32_16x16x32_bf16 v[42:45], v[130:133], v[192:195], v[42:45]
	v_mfma_f32_16x16x32_bf16 v[26:29], v[130:133], v[200:203], v[26:29]
	v_mfma_f32_16x16x32_bf16 v[26:29], v[134:137], v[204:207], v[26:29]
	v_mfma_f32_16x16x32_bf16 v[6:9], v[134:137], v[212:215], v[6:9]
	v_mfma_f32_16x16x32_bf16 v[6:9], v[130:133], v[208:211], v[6:9]
	v_mfma_f32_16x16x32_bf16 v[2:5], v[138:141], v[208:211], v[2:5]
	v_mfma_f32_16x16x32_bf16 v[2:5], v[142:145], v[212:215], v[2:5]
	v_mfma_f32_16x16x32_bf16 v[18:21], v[142:145], v[204:207], v[18:21]
	v_mfma_f32_16x16x32_bf16 v[18:21], v[138:141], v[200:203], v[18:21]
	v_mfma_f32_16x16x32_bf16 v[34:37], v[138:141], v[192:195], v[34:37]
	v_mfma_f32_16x16x32_bf16 v[34:37], v[142:145], v[196:199], v[34:37]
	v_mfma_f32_16x16x32_bf16 v[54:57], v[142:145], v[188:191], v[54:57]
	v_mfma_f32_16x16x32_bf16 v[54:57], v[138:141], v[180:183], v[54:57]
	v_mfma_f32_16x16x32_bf16 v[62:65], v[146:149], v[180:183], v[62:65]
	v_mfma_f32_16x16x32_bf16 v[62:65], v[150:153], v[188:191], v[62:65]
	v_mfma_f32_16x16x32_bf16 v[46:49], v[150:153], v[196:199], v[46:49]
	v_mfma_f32_16x16x32_bf16 v[46:49], v[146:149], v[192:195], v[46:49]
	v_mfma_f32_16x16x32_bf16 v[30:33], v[146:149], v[200:203], v[30:33]
	v_mfma_f32_16x16x32_bf16 v[30:33], v[150:153], v[204:207], v[30:33]
	v_mfma_f32_16x16x32_bf16 v[10:13], v[150:153], v[212:215], v[10:13]
	v_mfma_f32_16x16x32_bf16 v[10:13], v[146:149], v[208:211], v[10:13]
	v_mfma_f32_16x16x32_bf16 v[14:17], v[172:175], v[208:211], v[14:17]
	v_mfma_f32_16x16x32_bf16 v[14:17], v[176:179], v[212:215], v[14:17]
	v_mfma_f32_16x16x32_bf16 v[22:25], v[176:179], v[204:207], v[22:25]
	v_mfma_f32_16x16x32_bf16 v[22:25], v[172:175], v[200:203], v[22:25]
	v_mfma_f32_16x16x32_bf16 v[38:41], v[172:175], v[192:195], v[38:41]
	v_mfma_f32_16x16x32_bf16 v[38:41], v[176:179], v[196:199], v[38:41]
	v_mfma_f32_16x16x32_bf16 v[50:53], v[176:179], v[188:191], v[50:53]
	v_mfma_f32_16x16x32_bf16 v[50:53], v[172:175], v[180:183], v[50:53]
	s_barrier
	s_add_i32 s64, s64, 2
	s_add_u32 s18, s18, 0x100
	s_addc_u32 s19, s19, 0
	s_add_u32 s62, s62, 0x100
	s_addc_u32 s63, s63, 0
	s_cmpk_gt_u32 s64, 0xa9
	s_cbranch_scc0 .LBB0_1245
	s_and_b64 vcc, exec, s[12:13]
	s_cbranch_vccz .LBB0_1248
	v_lshl_or_b32 v172, s53, 8, v184
	v_lshl_add_u32 v176, s52, 8, v1
	v_ashrrev_i32_e32 v173, 31, v172
	v_lshlrev_b64 v[196:197], 1, v[172:173]
	v_ashrrev_i32_e32 v177, 31, v176
	v_lshl_add_u64 v[174:175], s[96:97], 0, v[196:197]
	v_lshlrev_b64 v[198:199], 13, v[176:177]
	v_lshl_add_u64 v[130:131], v[174:175], 0, v[198:199]
	global_load_dwordx4 v[188:191], v[130:131], off
	global_load_dwordx4 v[192:195], v[130:131], off offset:256
	v_or_b32_e32 v182, 16, v176
	v_or_b32_e32 v180, 32, v176
	v_or_b32_e32 v178, 48, v176
	v_ashrrev_i32_e32 v183, 31, v182
	v_ashrrev_i32_e32 v181, 31, v180
	v_ashrrev_i32_e32 v179, 31, v178
	v_lshlrev_b64 v[130:131], 13, v[182:183]
	v_lshlrev_b64 v[132:133], 13, v[180:181]
	v_lshlrev_b64 v[134:135], 13, v[178:179]
	v_lshl_add_u64 v[130:131], v[174:175], 0, v[130:131]
	v_lshl_add_u64 v[132:133], v[174:175], 0, v[132:133]
	v_lshl_add_u64 v[200:201], v[174:175], 0, v[134:135]
	global_load_dwordx4 v[150:153], v[130:131], off
	global_load_dwordx4 v[146:149], v[130:131], off offset:256
	global_load_dwordx4 v[142:145], v[132:133], off
	global_load_dwordx4 v[138:141], v[132:133], off offset:256
	global_load_dwordx4 v[134:137], v[200:201], off
	s_nop 0
	global_load_dwordx4 v[130:133], v[200:201], off offset:256
	s_barrier
	s_branch .Lepi_rest_1248

; __device__ __forceinline__ unsigned cvt_pk_bf16(float lo, float hi) { unsigned r; asm volatile("v_cvt_pk_bf16_f32 %0, %1, %2" : "=v"(r) : "v"(lo), "v"(hi)); return r; }
; __device__ __forceinline__ unsigned cvt_pk_bf16(float lo, float hi) { unsigned r; asm volatile("v_cvt_pk_bf16_f32 %0, %1, %2" : "=v"(r) : "v"(lo), "v"(hi)); return r; }
;     __device__ __forceinline__ void operator()(const f32x4 (&acc)[2][2][4][2], const Unit& u, int wr, int wc, int fr, int fq) const {
;     ...
;                     else { const u32x4 r = *(const u32x4*)((const bf16_t*)base + off);
;                         b0[m][bj] = (f32x4){__uint_as_float(r.x << 16), __uint_as_float(r.x & 0xffff0000u), __uint_as_float(r.y << 16), __uint_as_float(r.y & 0xffff0000u)};
;                         b1[m][bj] = (f32x4){__uint_as_float(r.z << 16), __uint_as_float(r.z & 0xffff0000u), __uint_as_float(r.w << 16), __uint_as_float(r.w & 0xffff0000u)}; } }
; #pragma unroll
;             for (int m = 0; m < 4; ++m) { const int row = row0 + ai * HALF + m * 16; const size_t off = (size_t)row * ldc + col0; f32x2 q2 = {0.f, 0.f};
; #pragma unroll
;                 for (int bj = 0; bj < 2; ++bj) { const f32x4 v0 = acc[ai][bj][m][0] + b0[m][bj], v1 = acc[ai][bj][m][1] + b1[m][bj];
;                     { const f32x2 e0 = {v0[0], v0[1]}, e1 = {v0[2], v0[3]}, e2 = {v1[0], v1[1]}, e3 = {v1[2], v1[3]}; q2 = e0 * e0 + q2; q2 = e1 * e1 + q2; q2 = e2 * e2 + q2; q2 = e3 * e3 + q2; }
;                     u32x4 w; w.x = cvt_pk_bf16(v0[0], v0[1]); w.y = cvt_pk_bf16(v0[2], v0[3]); w.z = cvt_pk_bf16(v1[0], v1[1]); w.w = cvt_pk_bf16(v1[2], v1[3]);
;                     *(u32x4*)(out + off + bj * HALF) = w; }
;                 float q = q2.x + q2.y; q += __shfl_xor(q, 16); q += __shfl_xor(q, 32);
;                 if (fq == 0) atomicAdd(ssq + row, (ssq_t)(q * SSQ_FIX + 0.5f)); }
.Lepi_rest_1248:
	v_and_b32_e32 v200, 64, v186
	v_xor_b32_e32 v187, 16, v186
	v_add_u32_e32 v200, 64, v200
	v_xor_b32_e32 v201, 32, v186
	v_cmp_lt_i32_e32 vcc, v187, v200
	v_lshl_add_u64 v[198:199], s[96:97], 0, v[198:199]
	v_lshl_add_u64 v[196:197], v[198:199], 0, v[196:197]
	v_cndmask_b32_e32 v187, v186, v187, vcc
	v_cmp_lt_i32_e32 vcc, v201, v200
	v_lshlrev_b32_e32 v187, 2, v187
	s_waitcnt vmcnt(0)
	v_lshlrev_b32_e32 v198, 16, v188
	v_and_b32_e32 v199, 0xffff0000, v188
	v_lshlrev_b32_e32 v188, 16, v189
	v_and_b32_e32 v189, 0xffff0000, v189
	v_cndmask_b32_e32 v206, v186, v201, vcc
	v_lshlrev_b32_e32 v200, 16, v190
	v_and_b32_e32 v201, 0xffff0000, v190
	v_lshlrev_b32_e32 v190, 16, v191
	v_and_b32_e32 v191, 0xffff0000, v191
	v_pk_add_f32 v[116:117], v[116:117], v[188:189]
	v_pk_add_f32 v[188:189], v[114:115], v[198:199]
	v_pk_add_f32 v[120:121], v[120:121], v[190:191]
	v_pk_mul_f32 v[190:191], v[116:117], v[116:117]
	v_pk_add_f32 v[118:119], v[118:119], v[200:201]
	v_cvt_pk_bf16_f32 v114, v188, v189
	v_cvt_pk_bf16_f32 v115, v116, v117
	v_pk_fma_f32 v[116:117], v[188:189], v[188:189], v[190:191]
	v_lshlrev_b32_e32 v202, 16, v192
	v_and_b32_e32 v203, 0xffff0000, v192
	v_pk_fma_f32 v[116:117], v[118:119], v[118:119], v[116:117]
	v_lshlrev_b32_e32 v192, 16, v193
	v_and_b32_e32 v193, 0xffff0000, v193
	v_pk_add_f32 v[122:123], v[122:123], v[202:203]
	v_pk_fma_f32 v[116:117], v[120:121], v[120:121], v[116:117]
	v_lshlrev_b32_e32 v204, 16, v194
	v_and_b32_e32 v205, 0xffff0000, v194
	v_pk_add_f32 v[124:125], v[124:125], v[192:193]
	v_pk_fma_f32 v[116:117], v[122:123], v[122:123], v[116:117]
	v_lshlrev_b32_e32 v194, 16, v195
	v_and_b32_e32 v195, 0xffff0000, v195
	v_pk_add_f32 v[126:127], v[126:127], v[204:205]
	v_pk_fma_f32 v[116:117], v[124:125], v[124:125], v[116:117]
	v_pk_add_f32 v[128:129], v[128:129], v[194:195]
	v_pk_fma_f32 v[116:117], v[126:127], v[126:127], v[116:117]
	s_nop 0
	v_pk_fma_f32 v[116:117], v[128:129], v[128:129], v[116:117]
	s_nop 0
	v_add_f32_e32 v188, v116, v117
	ds_bpermute_b32 v189, v187, v188
	v_cvt_pk_bf16_f32 v116, v118, v119
	v_cvt_pk_bf16_f32 v117, v120, v121
	global_store_dwordx4 v[196:197], v[114:117], off
	v_cvt_pk_bf16_f32 v118, v122, v123
	v_cvt_pk_bf16_f32 v119, v124, v125
	v_cvt_pk_bf16_f32 v120, v126, v127
	v_cvt_pk_bf16_f32 v121, v128, v129
	global_store_dwordx4 v[196:197], v[118:121], off offset:256
	s_waitcnt lgkmcnt(0)
	v_add_f32_e32 v115, v188, v189
	v_lshlrev_b32_e32 v114, 2, v206
	ds_bpermute_b32 v116, v114, v115
	s_and_saveexec_b64 s[16:17], s[0:1]
	s_cbranch_execz .LBB0_1250
	s_waitcnt lgkmcnt(0)
	v_add_f32_e32 v115, v115, v116
	v_fma_f32 v115, v115, s43, 0.5
	v_trunc_f32_e32 v115, v115
	v_mul_f32_e32 v116, 0x2f800000, v115
	v_floor_f32_e32 v117, v116
	v_fmac_f32_e32 v115, 0xcf800000, v117
	v_cvt_u32_f32_e32 v116, v115
	v_cvt_u32_f32_e32 v117, v117
	v_lshl_add_u64 v[118:119], v[176:177], 3, s[8:9]
	global_atomic_add_x2 v[118:119], v[116:117], off

; #define PG8_STAGE(bufoff, gbase, voff) do { _Pragma("unroll") for (int _i = 0; _i < 2; ++_i) \
;         __builtin_amdgcn_global_load_lds((const unsigned*)((const char*)(gbase) + (voff)[_i]), (PG8_LAS unsigned*)(lds + (bufoff) + ldsw + _i * 8192), 16, 0, 0); } while (0)
; #define PG8_LDA(dst, b, h) do { _Pragma("unroll") for (int m = 0; m < 4; ++m) _Pragma("unroll") for (int k = 0; k < 2; ++k) dst[m][k] = *(const PG8_LAS bf16x8*)(lds + PG8_SA(b, h) + aoff + m * 2048 + k * 1024); } while (0)
; #define PG8_LDB(dst, b, h) do { _Pragma("unroll") for (int n = 0; n < 2; ++n) _Pragma("unroll") for (int k = 0; k < 2; ++k) dst[n][k] = *(const PG8_LAS bf16x8*)(lds + PG8_SB(b, h) + boff + n * 2048 + k * 1024); } while (0)
; #define PG8_MMA(ai, bj, At, Bt) do { __builtin_amdgcn_s_setprio(1); _Pragma("unroll") for (int m = 0; m < 4; ++m) _Pragma("unroll") for (int n = 0; n < 2; ++n) _Pragma("unroll") for (int k = 0; k < 2; ++k) \
;         acc[ai][bj][m][n] = __builtin_amdgcn_mfma_f32_16x16x32_bf16(Bt[n][k], At[m][k], acc[ai][bj][m][n], 0, 0, 0); __builtin_amdgcn_s_setprio(0); } while (0)
; #define PG8_WAIT_V(n) asm volatile("s_waitcnt vmcnt(" #n ")" ::: "memory")
; #define PG8_WAIT_L(n) asm volatile("s_waitcnt lgkmcnt(" #n ")" ::: "memory")
; #define PG8_BAR __builtin_amdgcn_s_barrier()
; #define PG8_SCHED __builtin_amdgcn_sched_barrier(0)
; template <class Epi, class Sched, bool ALIGN_EPI = false, bool SP2 = false>
; __device__ __forceinline__ void gemm_phase(PG8_LAS unsigned char* lds, const Gemm g, const Sched& S, const Epi& E) {
;     ...
;             PG8_LDB(B0, 0, 0); PG8_LDB(B1, 0, 1); PG8_SCHED; PG8_LDA(At, 0, 0); PG8_STAGE(PG8_SA(1, 1), a1 + hstep, voffA);
;             PG8_WAIT_V(8); PG8_WAIT_L(0); PG8_BAR; PG8_MMA(0, 0, At, B0); PG8_MMA(0, 1, At, B1); PG8_BAR; PG8_SCHED;
;             PG8_LDA(At, 0, 1); PG8_STAGE(PG8_SB(0, 0), b2, voffB); PG8_STAGE(PG8_SB(0, 1), b2 + hstep, voffB); PG8_STAGE(PG8_SA(0, 0), a2, voffA);
;             PG8_WAIT_V(8); PG8_WAIT_L(0); PG8_BAR; PG8_MMA(1, 0, At, B0); PG8_MMA(1, 1, At, B1); PG8_BAR; PG8_SCHED;
.LBB0_1595:
	ds_read_b128 v[130:133], v241 offset:0
	ds_read_b128 v[134:137], v241 offset:1024
	ds_read_b128 v[138:141], v241 offset:2048
	ds_read_b128 v[142:145], v241 offset:3072
	ds_read_b128 v[146:149], v241 offset:16384
	ds_read_b128 v[150:153], v241 offset:17408
	ds_read_b128 v[172:175], v241 offset:18432
	ds_read_b128 v[176:179], v241 offset:19456
	s_add_u32 s24, s26, 0xfff00080
	s_addc_u32 s25, s27, -1
	s_cmp_eq_u32 s62, 60
	s_cselect_b32 s29, s15, s25
	s_cselect_b32 s28, s21, s24
	s_cselect_b32 s25, s13, s53
	s_cselect_b32 s24, s51, s52
	s_add_i32 m0, s23, 0xc000
	ds_read_b128 v[180:183], v185
	ds_read_b128 v[188:191], v185 offset:1024
	ds_read_b128 v[192:195], v185 offset:2048
	ds_read_b128 v[196:199], v185 offset:3072
	ds_read_b128 v[200:203], v185 offset:4096
	ds_read_b128 v[204:207], v185 offset:5120
	ds_read_b128 v[208:211], v185 offset:6144
	ds_read_b128 v[212:215], v185 offset:7168
	global_load_lds_dwordx4 v162, s[26:27]
	s_add_i32 m0, s23, 0xe000
	s_nop 0
	global_load_lds_dwordx4 v166, s[26:27]
	s_waitcnt vmcnt(8)
	s_waitcnt lgkmcnt(0)
	s_barrier
	s_waitcnt lgkmcnt(0)
	v_mfma_f32_16x16x32_bf16 v[114:117], v[130:133], v[180:183], v[114:117]
	v_mfma_f32_16x16x32_bf16 v[114:117], v[134:137], v[188:191], v[114:117]
	v_mfma_f32_16x16x32_bf16 v[106:109], v[134:137], v[196:199], v[106:109]
	v_mfma_f32_16x16x32_bf16 v[106:109], v[130:133], v[192:195], v[106:109]
	v_mfma_f32_16x16x32_bf16 v[90:93], v[130:133], v[200:203], v[90:93]
	v_mfma_f32_16x16x32_bf16 v[90:93], v[134:137], v[204:207], v[90:93]
	v_mfma_f32_16x16x32_bf16 v[74:77], v[134:137], v[212:215], v[74:77]
	v_mfma_f32_16x16x32_bf16 v[74:77], v[130:133], v[208:211], v[74:77]
	v_mfma_f32_16x16x32_bf16 v[66:69], v[138:141], v[208:211], v[66:69]
	v_mfma_f32_16x16x32_bf16 v[66:69], v[142:145], v[212:215], v[66:69]
	v_mfma_f32_16x16x32_bf16 v[82:85], v[142:145], v[204:207], v[82:85]
	v_mfma_f32_16x16x32_bf16 v[82:85], v[138:141], v[200:203], v[82:85]
	v_mfma_f32_16x16x32_bf16 v[98:101], v[138:141], v[192:195], v[98:101]
	v_mfma_f32_16x16x32_bf16 v[98:101], v[142:145], v[196:199], v[98:101]
	v_mfma_f32_16x16x32_bf16 v[118:121], v[142:145], v[188:191], v[118:121]
	v_mfma_f32_16x16x32_bf16 v[118:121], v[138:141], v[180:183], v[118:121]
	v_mfma_f32_16x16x32_bf16 v[122:125], v[146:149], v[180:183], v[122:125]
	v_mfma_f32_16x16x32_bf16 v[122:125], v[150:153], v[188:191], v[122:125]
	v_mfma_f32_16x16x32_bf16 v[110:113], v[150:153], v[196:199], v[110:113]
	v_mfma_f32_16x16x32_bf16 v[110:113], v[146:149], v[192:195], v[110:113]
	v_mfma_f32_16x16x32_bf16 v[94:97], v[146:149], v[200:203], v[94:97]
	v_mfma_f32_16x16x32_bf16 v[94:97], v[150:153], v[204:207], v[94:97]
	v_mfma_f32_16x16x32_bf16 v[78:81], v[150:153], v[212:215], v[78:81]
	v_mfma_f32_16x16x32_bf16 v[78:81], v[146:149], v[208:211], v[78:81]
	v_mfma_f32_16x16x32_bf16 v[70:73], v[172:175], v[208:211], v[70:73]
	v_mfma_f32_16x16x32_bf16 v[70:73], v[176:179], v[212:215], v[70:73]
	v_mfma_f32_16x16x32_bf16 v[86:89], v[176:179], v[204:207], v[86:89]
	v_mfma_f32_16x16x32_bf16 v[86:89], v[172:175], v[200:203], v[86:89]
	v_mfma_f32_16x16x32_bf16 v[102:105], v[172:175], v[192:195], v[102:105]
	v_mfma_f32_16x16x32_bf16 v[102:105], v[176:179], v[196:199], v[102:105]
	v_mfma_f32_16x16x32_bf16 v[126:129], v[176:179], v[188:191], v[126:129]
	v_mfma_f32_16x16x32_bf16 v[126:129], v[172:175], v[180:183], v[126:129]
	s_barrier
	s_add_i32 s33, s48, s36
	s_mov_b32 m0, s33
	ds_read_b128 v[180:183], v185 offset:16384
	ds_read_b128 v[188:191], v185 offset:17408
	ds_read_b128 v[192:195], v185 offset:18432
	ds_read_b128 v[196:199], v185 offset:19456
	ds_read_b128 v[200:203], v185 offset:20480
	ds_read_b128 v[204:207], v185 offset:21504
	ds_read_b128 v[208:211], v185 offset:22528
	ds_read_b128 v[212:215], v185 offset:23552
	global_load_lds_dwordx4 v156, s[24:25]
	s_add_i32 m0, s33, 0x2000
	s_add_u32 s64, s24, 0x100000
	s_addc_u32 s65, s25, 0
	s_add_i32 s33, s49, s36
	global_load_lds_dwordx4 v160, s[24:25]
	s_mov_b32 m0, s33
	s_add_u32 s100, s28, 0x80
	s_addc_u32 s101, s29, 0
	global_load_lds_dwordx4 v156, s[64:65]
	s_add_i32 m0, s33, 0x2000
	s_nop 0
	global_load_lds_dwordx4 v160, s[64:65]
	s_mov_b32 m0, s23
	s_nop 0
	global_load_lds_dwordx4 v154, s[28:29]
	s_mov_b32 m0, s37
	s_nop 0
	global_load_lds_dwordx4 v158, s[28:29]
	s_waitcnt vmcnt(8)
	s_waitcnt lgkmcnt(0)
	s_barrier
	s_waitcnt lgkmcnt(0)
	v_mfma_f32_16x16x32_bf16 v[58:61], v[130:133], v[180:183], v[58:61]
	v_mfma_f32_16x16x32_bf16 v[58:61], v[134:137], v[188:191], v[58:61]
	v_mfma_f32_16x16x32_bf16 v[42:45], v[134:137], v[196:199], v[42:45]
	v_mfma_f32_16x16x32_bf16 v[42:45], v[130:133], v[192:195], v[42:45]
	v_mfma_f32_16x16x32_bf16 v[26:29], v[130:133], v[200:203], v[26:29]
	v_mfma_f32_16x16x32_bf16 v[26:29], v[134:137], v[204:207], v[26:29]
	v_mfma_f32_16x16x32_bf16 v[6:9], v[134:137], v[212:215], v[6:9]
	v_mfma_f32_16x16x32_bf16 v[6:9], v[130:133], v[208:211], v[6:9]
	v_mfma_f32_16x16x32_bf16 v[2:5], v[138:141], v[208:211], v[2:5]
	v_mfma_f32_16x16x32_bf16 v[2:5], v[142:145], v[212:215], v[2:5]
	v_mfma_f32_16x16x32_bf16 v[18:21], v[142:145], v[204:207], v[18:21]
	v_mfma_f32_16x16x32_bf16 v[18:21], v[138:141], v[200:203], v[18:21]
	v_mfma_f32_16x16x32_bf16 v[34:37], v[138:141], v[192:195], v[34:37]
	v_mfma_f32_16x16x32_bf16 v[34:37], v[142:145], v[196:199], v[34:37]
	v_mfma_f32_16x16x32_bf16 v[54:57], v[142:145], v[188:191], v[54:57]
	v_mfma_f32_16x16x32_bf16 v[54:57], v[138:141], v[180:183], v[54:57]
	v_mfma_f32_16x16x32_bf16 v[62:65], v[146:149], v[180:183], v[62:65]
	v_mfma_f32_16x16x32_bf16 v[62:65], v[150:153], v[188:191], v[62:65]
	v_mfma_f32_16x16x32_bf16 v[46:49], v[150:153], v[196:199], v[46:49]
	v_mfma_f32_16x16x32_bf16 v[46:49], v[146:149], v[192:195], v[46:49]
	v_mfma_f32_16x16x32_bf16 v[30:33], v[146:149], v[200:203], v[30:33]
	v_mfma_f32_16x16x32_bf16 v[30:33], v[150:153], v[204:207], v[30:33]
	v_mfma_f32_16x16x32_bf16 v[10:13], v[150:153], v[212:215], v[10:13]
	v_mfma_f32_16x16x32_bf16 v[10:13], v[146:149], v[208:211], v[10:13]
	v_mfma_f32_16x16x32_bf16 v[14:17], v[172:175], v[208:211], v[14:17]
	v_mfma_f32_16x16x32_bf16 v[14:17], v[176:179], v[212:215], v[14:17]
	v_mfma_f32_16x16x32_bf16 v[22:25], v[176:179], v[204:207], v[22:25]
	v_mfma_f32_16x16x32_bf16 v[22:25], v[172:175], v[200:203], v[22:25]
	v_mfma_f32_16x16x32_bf16 v[38:41], v[172:175], v[192:195], v[38:41]
	v_mfma_f32_16x16x32_bf16 v[38:41], v[176:179], v[196:199], v[38:41]
	v_mfma_f32_16x16x32_bf16 v[50:53], v[176:179], v[188:191], v[50:53]
	v_mfma_f32_16x16x32_bf16 v[50:53], v[172:175], v[180:183], v[50:53]
	s_barrier
; #define PG8_STAGE(bufoff, gbase, voff) do { _Pragma("unroll") for (int _i = 0; _i < 2; ++_i) \
;         __builtin_amdgcn_global_load_lds((const unsigned*)((const char*)(gbase) + (voff)[_i]), (PG8_LAS unsigned*)(lds + (bufoff) + ldsw + _i * 8192), 16, 0, 0); } while (0)
; #define PG8_LDA(dst, b, h) do { _Pragma("unroll") for (int m = 0; m < 4; ++m) _Pragma("unroll") for (int k = 0; k < 2; ++k) dst[m][k] = *(const PG8_LAS bf16x8*)(lds + PG8_SA(b, h) + aoff + m * 2048 + k * 1024); } while (0)
; #define PG8_LDB(dst, b, h) do { _Pragma("unroll") for (int n = 0; n < 2; ++n) _Pragma("unroll") for (int k = 0; k < 2; ++k) dst[n][k] = *(const PG8_LAS bf16x8*)(lds + PG8_SB(b, h) + boff + n * 2048 + k * 1024); } while (0)
; #define PG8_MMA(ai, bj, At, Bt) do { __builtin_amdgcn_s_setprio(1); _Pragma("unroll") for (int m = 0; m < 4; ++m) _Pragma("unroll") for (int n = 0; n < 2; ++n) _Pragma("unroll") for (int k = 0; k < 2; ++k) \
;         acc[ai][bj][m][n] = __builtin_amdgcn_mfma_f32_16x16x32_bf16(Bt[n][k], At[m][k], acc[ai][bj][m][n], 0, 0, 0); __builtin_amdgcn_s_setprio(0); } while (0)
; #define PG8_WAIT_V(n) asm volatile("s_waitcnt vmcnt(" #n ")" ::: "memory")
; #define PG8_WAIT_L(n) asm volatile("s_waitcnt lgkmcnt(" #n ")" ::: "memory")
; #define PG8_BAR __builtin_amdgcn_s_barrier()
; #define PG8_SCHED __builtin_amdgcn_sched_barrier(0)
; template <class Epi, class Sched, bool ALIGN_EPI = false, bool SP2 = false>
; __device__ __forceinline__ void gemm_phase(PG8_LAS unsigned char* lds, const Gemm g, const Sched& S, const Epi& E) {
;     ...
;             PG8_LDB(B0, 1, 0); PG8_LDB(B1, 1, 1); PG8_SCHED; PG8_LDA(At, 1, 0); PG8_STAGE(PG8_SA(0, 1), a2 + hstep, voffA);
;             PG8_WAIT_V(8); PG8_WAIT_L(0); PG8_BAR; PG8_MMA(0, 0, At, B0); PG8_MMA(0, 1, At, B1); PG8_BAR; PG8_SCHED;
;             PG8_LDA(At, 1, 1); PG8_STAGE(PG8_SB(1, 0), b3, voffB); PG8_STAGE(PG8_SB(1, 1), b3 + hstep, voffB); PG8_STAGE(PG8_SA(1, 0), a3, voffA);
;             PG8_WAIT_V(8); PG8_WAIT_L(0); PG8_BAR; PG8_MMA(1, 0, At, B0); PG8_MMA(1, 1, At, B1); PG8_BAR; PG8_SCHED;
	s_add_i32 s33, 0, 0x18000
	s_add_i32 s42, 0, 0x1c000
	ds_read_b128 v[130:133], v241 offset:32768
	ds_read_b128 v[134:137], v241 offset:33792
	ds_read_b128 v[138:141], v241 offset:34816
	ds_read_b128 v[142:145], v241 offset:35840
	ds_read_b128 v[146:149], v241 offset:49152
	ds_read_b128 v[150:153], v241 offset:50176
	ds_read_b128 v[172:175], v241 offset:51200
	ds_read_b128 v[176:179], v241 offset:52224
	s_add_u32 s28, s28, 0x100000
	s_addc_u32 s29, s29, 0
	s_mov_b32 m0, s40
	ds_read_b128 v[180:183], v185 offset:32768
	ds_read_b128 v[188:191], v185 offset:33792
	ds_read_b128 v[192:195], v185 offset:34816
	ds_read_b128 v[196:199], v185 offset:35840
	ds_read_b128 v[200:203], v185 offset:36864
	ds_read_b128 v[204:207], v185 offset:37888
	ds_read_b128 v[208:211], v185 offset:38912
	ds_read_b128 v[212:215], v185 offset:39936
	global_load_lds_dwordx4 v154, s[28:29]
	s_mov_b32 m0, s41
	s_nop 0
	global_load_lds_dwordx4 v158, s[28:29]
	s_waitcnt vmcnt(8)
	s_waitcnt lgkmcnt(0)
	s_barrier
	s_waitcnt lgkmcnt(0)
	v_mfma_f32_16x16x32_bf16 v[114:117], v[130:133], v[180:183], v[114:117]
	v_mfma_f32_16x16x32_bf16 v[114:117], v[134:137], v[188:191], v[114:117]
	v_mfma_f32_16x16x32_bf16 v[106:109], v[134:137], v[196:199], v[106:109]
	v_mfma_f32_16x16x32_bf16 v[106:109], v[130:133], v[192:195], v[106:109]
	v_mfma_f32_16x16x32_bf16 v[90:93], v[130:133], v[200:203], v[90:93]
	v_mfma_f32_16x16x32_bf16 v[90:93], v[134:137], v[204:207], v[90:93]
	v_mfma_f32_16x16x32_bf16 v[74:77], v[134:137], v[212:215], v[74:77]
	v_mfma_f32_16x16x32_bf16 v[74:77], v[130:133], v[208:211], v[74:77]
	v_mfma_f32_16x16x32_bf16 v[66:69], v[138:141], v[208:211], v[66:69]
	v_mfma_f32_16x16x32_bf16 v[66:69], v[142:145], v[212:215], v[66:69]
	v_mfma_f32_16x16x32_bf16 v[82:85], v[142:145], v[204:207], v[82:85]
	v_mfma_f32_16x16x32_bf16 v[82:85], v[138:141], v[200:203], v[82:85]
	v_mfma_f32_16x16x32_bf16 v[98:101], v[138:141], v[192:195], v[98:101]
	v_mfma_f32_16x16x32_bf16 v[98:101], v[142:145], v[196:199], v[98:101]
	v_mfma_f32_16x16x32_bf16 v[118:121], v[142:145], v[188:191], v[118:121]
	v_mfma_f32_16x16x32_bf16 v[118:121], v[138:141], v[180:183], v[118:121]
	v_mfma_f32_16x16x32_bf16 v[122:125], v[146:149], v[180:183], v[122:125]
	v_mfma_f32_16x16x32_bf16 v[122:125], v[150:153], v[188:191], v[122:125]
	v_mfma_f32_16x16x32_bf16 v[110:113], v[150:153], v[196:199], v[110:113]
	v_mfma_f32_16x16x32_bf16 v[110:113], v[146:149], v[192:195], v[110:113]
	v_mfma_f32_16x16x32_bf16 v[94:97], v[146:149], v[200:203], v[94:97]
	v_mfma_f32_16x16x32_bf16 v[94:97], v[150:153], v[204:207], v[94:97]
	v_mfma_f32_16x16x32_bf16 v[78:81], v[150:153], v[212:215], v[78:81]
	v_mfma_f32_16x16x32_bf16 v[78:81], v[146:149], v[208:211], v[78:81]
	v_mfma_f32_16x16x32_bf16 v[70:73], v[172:175], v[208:211], v[70:73]
	v_mfma_f32_16x16x32_bf16 v[70:73], v[176:179], v[212:215], v[70:73]
	v_mfma_f32_16x16x32_bf16 v[86:89], v[176:179], v[204:207], v[86:89]
	v_mfma_f32_16x16x32_bf16 v[86:89], v[172:175], v[200:203], v[86:89]
	v_mfma_f32_16x16x32_bf16 v[102:105], v[172:175], v[192:195], v[102:105]
	v_mfma_f32_16x16x32_bf16 v[102:105], v[176:179], v[196:199], v[102:105]
	v_mfma_f32_16x16x32_bf16 v[126:129], v[176:179], v[188:191], v[126:129]
	v_mfma_f32_16x16x32_bf16 v[126:129], v[172:175], v[180:183], v[126:129]
	s_barrier
	s_add_i32 s28, s33, s36
	s_add_i32 m0, s28, 0xffffff80
	ds_read_b128 v[180:183], v185 offset:49152
	ds_read_b128 v[188:191], v185 offset:50176
	ds_read_b128 v[192:195], v185 offset:51200
	ds_read_b128 v[196:199], v185 offset:52224
	ds_read_b128 v[200:203], v185 offset:53248
	ds_read_b128 v[204:207], v185 offset:54272
	ds_read_b128 v[208:211], v185 offset:55296
	ds_read_b128 v[212:215], v185 offset:56320
	global_load_lds_dwordx4 v156, s[24:25] offset:128
	s_add_i32 m0, s28, 0x1f80
	s_add_i32 s28, s42, s36
	global_load_lds_dwordx4 v160, s[24:25] offset:128
	s_add_u32 s24, s24, 0x100080
	s_addc_u32 s25, s25, 0
	s_mov_b32 m0, s28
	s_nop 0
	global_load_lds_dwordx4 v156, s[24:25]
	s_add_i32 m0, s28, 0x2000
	s_nop 0
	global_load_lds_dwordx4 v160, s[24:25]
	s_mov_b32 m0, s44
	s_nop 0
	global_load_lds_dwordx4 v154, s[100:101]
	s_mov_b32 m0, s45
	s_nop 0
	global_load_lds_dwordx4 v158, s[100:101]
	s_waitcnt vmcnt(8)
	s_waitcnt lgkmcnt(0)
	s_barrier
; #define PG8_STAGE(bufoff, gbase, voff) do { _Pragma("unroll") for (int _i = 0; _i < 2; ++_i) \
;         __builtin_amdgcn_global_load_lds((const unsigned*)((const char*)(gbase) + (voff)[_i]), (PG8_LAS unsigned*)(lds + (bufoff) + ldsw + _i * 8192), 16, 0, 0); } while (0)
; #define PG8_LDA(dst, b, h) do { _Pragma("unroll") for (int m = 0; m < 4; ++m) _Pragma("unroll") for (int k = 0; k < 2; ++k) dst[m][k] = *(const PG8_LAS bf16x8*)(lds + PG8_SA(b, h) + aoff + m * 2048 + k * 1024); } while (0)
; #define PG8_MMA(ai, bj, At, Bt) do { __builtin_amdgcn_s_setprio(1); _Pragma("unroll") for (int m = 0; m < 4; ++m) _Pragma("unroll") for (int n = 0; n < 2; ++n) _Pragma("unroll") for (int k = 0; k < 2; ++k) \
;         acc[ai][bj][m][n] = __builtin_amdgcn_mfma_f32_16x16x32_bf16(Bt[n][k], At[m][k], acc[ai][bj][m][n], 0, 0, 0); __builtin_amdgcn_s_setprio(0); } while (0)
; #define PG8_WAIT_V(n) asm volatile("s_waitcnt vmcnt(" #n ")" ::: "memory")
;     __device__ __forceinline__ void operator()(const f32x4 (&acc)[2][2][4][2], const Unit& u, int wr, int wc, int fr, int fq) const {
;     ...
;                 for (int bj = 0; bj < 2; ++bj) { const size_t off = (size_t)(row0 + ai * HALF + m * 16) * ldc + col0 + bj * HALF;
;                     if (BASE_F32) { const float* bp = (const float*)base + off; b0[m][bj] = *(const f32x4*)bp; b1[m][bj] = *(const f32x4*)(bp + 4); }
;                     else { const u32x4 r = *(const u32x4*)((const bf16_t*)base + off);
;                         b0[m][bj] = (f32x4){__uint_as_float(r.x << 16), __uint_as_float(r.x & 0xffff0000u), __uint_as_float(r.y << 16), __uint_as_float(r.y & 0xffff0000u)};
;                         b1[m][bj] = (f32x4){__uint_as_float(r.z << 16), __uint_as_float(r.z & 0xffff0000u), __uint_as_float(r.w << 16), __uint_as_float(r.w & 0xffff0000u)}; } }
; template <class Epi, class Sched, bool ALIGN_EPI = false, bool SP2 = false>
; __device__ __forceinline__ void gemm_phase(PG8_LAS unsigned char* lds, const Gemm g, const Sched& S, const Epi& E) {
;     ...
;             PG8_WAIT_V(8); PG8_WAIT_L(0); PG8_BAR; PG8_MMA(0, 0, At, B0); PG8_MMA(0, 1, At, B1); PG8_BAR; PG8_SCHED;
;             PG8_LDA(At, 1, 1); PG8_STAGE(PG8_SB(1, 0), b3, voffB); PG8_STAGE(PG8_SB(1, 1), b3 + hstep, voffB); PG8_STAGE(PG8_SA(1, 0), a3, voffA);
;             PG8_WAIT_V(8); PG8_WAIT_L(0); PG8_BAR; PG8_MMA(1, 0, At, B0); PG8_MMA(1, 1, At, B1); PG8_BAR; PG8_SCHED;
	s_waitcnt lgkmcnt(0)
	v_mfma_f32_16x16x32_bf16 v[58:61], v[130:133], v[180:183], v[58:61]
	v_mfma_f32_16x16x32_bf16 v[58:61], v[134:137], v[188:191], v[58:61]
	v_mfma_f32_16x16x32_bf16 v[42:45], v[134:137], v[196:199], v[42:45]
	v_mfma_f32_16x16x32_bf16 v[42:45], v[130:133], v[192:195], v[42:45]
	v_mfma_f32_16x16x32_bf16 v[26:29], v[130:133], v[200:203], v[26:29]
	v_mfma_f32_16x16x32_bf16 v[26:29], v[134:137], v[204:207], v[26:29]
	v_mfma_f32_16x16x32_bf16 v[6:9], v[134:137], v[212:215], v[6:9]
	v_mfma_f32_16x16x32_bf16 v[6:9], v[130:133], v[208:211], v[6:9]
	v_mfma_f32_16x16x32_bf16 v[2:5], v[138:141], v[208:211], v[2:5]
	v_mfma_f32_16x16x32_bf16 v[2:5], v[142:145], v[212:215], v[2:5]
	v_mfma_f32_16x16x32_bf16 v[18:21], v[142:145], v[204:207], v[18:21]
	v_mfma_f32_16x16x32_bf16 v[18:21], v[138:141], v[200:203], v[18:21]
	v_mfma_f32_16x16x32_bf16 v[34:37], v[138:141], v[192:195], v[34:37]
	v_mfma_f32_16x16x32_bf16 v[34:37], v[142:145], v[196:199], v[34:37]
	v_mfma_f32_16x16x32_bf16 v[54:57], v[142:145], v[188:191], v[54:57]
	v_mfma_f32_16x16x32_bf16 v[54:57], v[138:141], v[180:183], v[54:57]
	v_mfma_f32_16x16x32_bf16 v[62:65], v[146:149], v[180:183], v[62:65]
	v_mfma_f32_16x16x32_bf16 v[62:65], v[150:153], v[188:191], v[62:65]
	v_mfma_f32_16x16x32_bf16 v[46:49], v[150:153], v[196:199], v[46:49]
	v_mfma_f32_16x16x32_bf16 v[46:49], v[146:149], v[192:195], v[46:49]
	v_mfma_f32_16x16x32_bf16 v[30:33], v[146:149], v[200:203], v[30:33]
	v_mfma_f32_16x16x32_bf16 v[30:33], v[150:153], v[204:207], v[30:33]
	v_mfma_f32_16x16x32_bf16 v[10:13], v[150:153], v[212:215], v[10:13]
	v_mfma_f32_16x16x32_bf16 v[10:13], v[146:149], v[208:211], v[10:13]
	v_mfma_f32_16x16x32_bf16 v[14:17], v[172:175], v[208:211], v[14:17]
	v_mfma_f32_16x16x32_bf16 v[14:17], v[176:179], v[212:215], v[14:17]
	v_mfma_f32_16x16x32_bf16 v[22:25], v[176:179], v[204:207], v[22:25]
	v_mfma_f32_16x16x32_bf16 v[22:25], v[172:175], v[200:203], v[22:25]
	v_mfma_f32_16x16x32_bf16 v[38:41], v[172:175], v[192:195], v[38:41]
	v_mfma_f32_16x16x32_bf16 v[38:41], v[176:179], v[196:199], v[38:41]
	v_mfma_f32_16x16x32_bf16 v[50:53], v[176:179], v[188:191], v[50:53]
	v_mfma_f32_16x16x32_bf16 v[50:53], v[172:175], v[180:183], v[50:53]
	s_barrier
	s_add_i32 s62, s62, 2
	s_add_u32 s26, s26, 0x100
	s_addc_u32 s27, s27, 0
	s_add_u32 s52, s52, 0x100
	s_addc_u32 s53, s53, 0
	s_cmp_gt_u32 s62, 61
	s_cbranch_scc0 .LBB0_1595
	s_and_b64 vcc, exec, s[10:11]
	s_cbranch_vccz .LBB0_1598
	v_lshl_or_b32 v172, s22, 8, v184
	v_lshl_add_u32 v176, s20, 8, v1
	v_ashrrev_i32_e32 v173, 31, v172
	v_lshlrev_b64 v[196:197], 1, v[172:173]
	v_ashrrev_i32_e32 v177, 31, v176
	v_lshl_add_u64 v[174:175], s[96:97], 0, v[196:197]
	v_lshlrev_b64 v[198:199], 13, v[176:177]
	v_lshl_add_u64 v[130:131], v[174:175], 0, v[198:199]
	global_load_dwordx4 v[188:191], v[130:131], off
	global_load_dwordx4 v[192:195], v[130:131], off offset:256
	v_or_b32_e32 v182, 16, v176
	v_or_b32_e32 v180, 32, v176
	v_or_b32_e32 v178, 48, v176
	v_ashrrev_i32_e32 v183, 31, v182
	v_ashrrev_i32_e32 v181, 31, v180
	v_ashrrev_i32_e32 v179, 31, v178
	v_lshlrev_b64 v[130:131], 13, v[182:183]
	v_lshlrev_b64 v[132:133], 13, v[180:181]
	v_lshlrev_b64 v[134:135], 13, v[178:179]
	v_lshl_add_u64 v[130:131], v[174:175], 0, v[130:131]
	v_lshl_add_u64 v[132:133], v[174:175], 0, v[132:133]
	v_lshl_add_u64 v[200:201], v[174:175], 0, v[134:135]
	global_load_dwordx4 v[150:153], v[130:131], off
	global_load_dwordx4 v[146:149], v[130:131], off offset:256
	global_load_dwordx4 v[142:145], v[132:133], off
	global_load_dwordx4 v[138:141], v[132:133], off offset:256
	global_load_dwordx4 v[134:137], v[200:201], off
	s_nop 0
	global_load_dwordx4 v[130:133], v[200:201], off offset:256
	s_barrier
	s_branch .Lepi_rest_1598

; __device__ __forceinline__ unsigned cvt_pk_bf16(float lo, float hi) { unsigned r; asm volatile("v_cvt_pk_bf16_f32 %0, %1, %2" : "=v"(r) : "v"(lo), "v"(hi)); return r; }
; __device__ __forceinline__ unsigned cvt_pk_bf16(float lo, float hi) { unsigned r; asm volatile("v_cvt_pk_bf16_f32 %0, %1, %2" : "=v"(r) : "v"(lo), "v"(hi)); return r; }
;     __device__ __forceinline__ void operator()(const f32x4 (&acc)[2][2][4][2], const Unit& u, int wr, int wc, int fr, int fq) const {
;     ...
;                     else { const u32x4 r = *(const u32x4*)((const bf16_t*)base + off);
;                         b0[m][bj] = (f32x4){__uint_as_float(r.x << 16), __uint_as_float(r.x & 0xffff0000u), __uint_as_float(r.y << 16), __uint_as_float(r.y & 0xffff0000u)};
;                         b1[m][bj] = (f32x4){__uint_as_float(r.z << 16), __uint_as_float(r.z & 0xffff0000u), __uint_as_float(r.w << 16), __uint_as_float(r.w & 0xffff0000u)}; } }
; #pragma unroll
;             for (int m = 0; m < 4; ++m) { const int row = row0 + ai * HALF + m * 16; const size_t off = (size_t)row * ldc + col0; f32x2 q2 = {0.f, 0.f};
; #pragma unroll
;                 for (int bj = 0; bj < 2; ++bj) { const f32x4 v0 = acc[ai][bj][m][0] + b0[m][bj], v1 = acc[ai][bj][m][1] + b1[m][bj];
;                     { const f32x2 e0 = {v0[0], v0[1]}, e1 = {v0[2], v0[3]}, e2 = {v1[0], v1[1]}, e3 = {v1[2], v1[3]}; q2 = e0 * e0 + q2; q2 = e1 * e1 + q2; q2 = e2 * e2 + q2; q2 = e3 * e3 + q2; }
;                     u32x4 w; w.x = cvt_pk_bf16(v0[0], v0[1]); w.y = cvt_pk_bf16(v0[2], v0[3]); w.z = cvt_pk_bf16(v1[0], v1[1]); w.w = cvt_pk_bf16(v1[2], v1[3]);
;                     *(u32x4*)(out + off + bj * HALF) = w; }
;                 float q = q2.x + q2.y; q += __shfl_xor(q, 16); q += __shfl_xor(q, 32);
;                 if (fq == 0) atomicAdd(ssq + row, (ssq_t)(q * SSQ_FIX + 0.5f)); }
.Lepi_rest_1598:
	v_and_b32_e32 v200, 64, v186
	v_xor_b32_e32 v187, 16, v186
	v_add_u32_e32 v200, 64, v200
	v_xor_b32_e32 v201, 32, v186
	v_cmp_lt_i32_e32 vcc, v187, v200
	v_lshl_add_u64 v[198:199], s[96:97], 0, v[198:199]
	v_lshl_add_u64 v[196:197], v[198:199], 0, v[196:197]
	v_cndmask_b32_e32 v187, v186, v187, vcc
	v_cmp_lt_i32_e32 vcc, v201, v200
	v_lshlrev_b32_e32 v187, 2, v187
	s_waitcnt vmcnt(0)
	v_lshlrev_b32_e32 v198, 16, v188
	v_and_b32_e32 v199, 0xffff0000, v188
	v_lshlrev_b32_e32 v188, 16, v189
	v_and_b32_e32 v189, 0xffff0000, v189
	v_cndmask_b32_e32 v206, v186, v201, vcc
	v_lshlrev_b32_e32 v200, 16, v190
	v_and_b32_e32 v201, 0xffff0000, v190
	v_lshlrev_b32_e32 v190, 16, v191
	v_and_b32_e32 v191, 0xffff0000, v191
	v_pk_add_f32 v[116:117], v[116:117], v[188:189]
	v_pk_add_f32 v[188:189], v[114:115], v[198:199]
	v_pk_add_f32 v[120:121], v[120:121], v[190:191]
	v_pk_mul_f32 v[190:191], v[116:117], v[116:117]
	v_pk_add_f32 v[118:119], v[118:119], v[200:201]
	v_cvt_pk_bf16_f32 v114, v188, v189
	v_cvt_pk_bf16_f32 v115, v116, v117
	v_pk_fma_f32 v[116:117], v[188:189], v[188:189], v[190:191]
	v_lshlrev_b32_e32 v202, 16, v192
	v_and_b32_e32 v203, 0xffff0000, v192
	v_pk_fma_f32 v[116:117], v[118:119], v[118:119], v[116:117]
	v_lshlrev_b32_e32 v192, 16, v193
	v_and_b32_e32 v193, 0xffff0000, v193
	v_pk_add_f32 v[122:123], v[122:123], v[202:203]
	v_pk_fma_f32 v[116:117], v[120:121], v[120:121], v[116:117]
	v_lshlrev_b32_e32 v204, 16, v194
	v_and_b32_e32 v205, 0xffff0000, v194
	v_pk_add_f32 v[124:125], v[124:125], v[192:193]
	v_pk_fma_f32 v[116:117], v[122:123], v[122:123], v[116:117]
	v_lshlrev_b32_e32 v194, 16, v195
	v_and_b32_e32 v195, 0xffff0000, v195
	v_pk_add_f32 v[126:127], v[126:127], v[204:205]
	v_pk_fma_f32 v[116:117], v[124:125], v[124:125], v[116:117]
	v_pk_add_f32 v[128:129], v[128:129], v[194:195]
	v_pk_fma_f32 v[116:117], v[126:127], v[126:127], v[116:117]
	s_nop 0
	v_pk_fma_f32 v[116:117], v[128:129], v[128:129], v[116:117]
	s_nop 0
	v_add_f32_e32 v188, v116, v117
	ds_bpermute_b32 v189, v187, v188
	v_cvt_pk_bf16_f32 v116, v118, v119
	v_cvt_pk_bf16_f32 v117, v120, v121
	global_store_dwordx4 v[196:197], v[114:117], off
	v_cvt_pk_bf16_f32 v118, v122, v123
	v_cvt_pk_bf16_f32 v119, v124, v125
	v_cvt_pk_bf16_f32 v120, v126, v127
	v_cvt_pk_bf16_f32 v121, v128, v129
	global_store_dwordx4 v[196:197], v[118:121], off offset:256
	s_waitcnt lgkmcnt(0)
	v_add_f32_e32 v115, v188, v189
	v_lshlrev_b32_e32 v114, 2, v206
	ds_bpermute_b32 v116, v114, v115
	s_and_saveexec_b64 s[20:21], s[0:1]
	s_cbranch_execz .LBB0_1600
	s_waitcnt lgkmcnt(0)
	v_add_f32_e32 v115, v115, v116
	v_fma_f32 v115, v115, s50, 0.5
	v_trunc_f32_e32 v115, v115
	v_mul_f32_e32 v116, 0x2f800000, v115
	v_floor_f32_e32 v117, v116
	v_fmac_f32_e32 v115, 0xcf800000, v117
	v_cvt_u32_f32_e32 v116, v115
	v_cvt_u32_f32_e32 v117, v117
	v_lshl_add_u64 v[118:119], v[176:177], 3, s[6:7]
	global_atomic_add_x2 v[118:119], v[116:117], off

; #define PG8_STAGE(bufoff, gbase, voff) do { _Pragma("unroll") for (int _i = 0; _i < 2; ++_i) \
;         __builtin_amdgcn_global_load_lds((const unsigned*)((const char*)(gbase) + (voff)[_i]), (PG8_LAS unsigned*)(lds + (bufoff) + ldsw + _i * 8192), 16, 0, 0); } while (0)
; #define PG8_LDA(dst, b, h) do { _Pragma("unroll") for (int m = 0; m < 4; ++m) _Pragma("unroll") for (int k = 0; k < 2; ++k) dst[m][k] = *(const PG8_LAS bf16x8*)(lds + PG8_SA(b, h) + aoff + m * 2048 + k * 1024); } while (0)
; #define PG8_LDB(dst, b, h) do { _Pragma("unroll") for (int n = 0; n < 2; ++n) _Pragma("unroll") for (int k = 0; k < 2; ++k) dst[n][k] = *(const PG8_LAS bf16x8*)(lds + PG8_SB(b, h) + boff + n * 2048 + k * 1024); } while (0)
; #define PG8_MMA(ai, bj, At, Bt) do { __builtin_amdgcn_s_setprio(1); _Pragma("unroll") for (int m = 0; m < 4; ++m) _Pragma("unroll") for (int n = 0; n < 2; ++n) _Pragma("unroll") for (int k = 0; k < 2; ++k) \
;         acc[ai][bj][m][n] = __builtin_amdgcn_mfma_f32_16x16x32_bf16(Bt[n][k], At[m][k], acc[ai][bj][m][n], 0, 0, 0); __builtin_amdgcn_s_setprio(0); } while (0)
; #define PG8_WAIT_V(n) asm volatile("s_waitcnt vmcnt(" #n ")" ::: "memory")
; #define PG8_WAIT_L(n) asm volatile("s_waitcnt lgkmcnt(" #n ")" ::: "memory")
; #define PG8_BAR __builtin_amdgcn_s_barrier()
; #define PG8_SCHED __builtin_amdgcn_sched_barrier(0)
; template <class Epi, class Sched, bool ALIGN_EPI = false, bool SP2 = false>
; __device__ __forceinline__ void gemm_phase(PG8_LAS unsigned char* lds, const Gemm g, const Sched& S, const Epi& E) {
;     ...
;             PG8_LDB(B0, 0, 0); PG8_LDB(B1, 0, 1); PG8_SCHED; PG8_LDA(At, 0, 0); PG8_STAGE(PG8_SA(1, 1), a1 + hstep, voffA);
;             PG8_WAIT_V(8); PG8_WAIT_L(0); PG8_BAR; PG8_MMA(0, 0, At, B0); PG8_MMA(0, 1, At, B1); PG8_BAR; PG8_SCHED;
;             PG8_LDA(At, 0, 1); PG8_STAGE(PG8_SB(0, 0), b2, voffB); PG8_STAGE(PG8_SB(0, 1), b2 + hstep, voffB); PG8_STAGE(PG8_SA(0, 0), a2, voffA);
;             PG8_WAIT_V(8); PG8_WAIT_L(0); PG8_BAR; PG8_MMA(1, 0, At, B0); PG8_MMA(1, 1, At, B1); PG8_BAR; PG8_SCHED;
.LBB0_1801:
	ds_read_b128 v[130:133], v241 offset:0
	ds_read_b128 v[134:137], v241 offset:1024
	ds_read_b128 v[138:141], v241 offset:2048
	ds_read_b128 v[142:145], v241 offset:3072
	ds_read_b128 v[146:149], v241 offset:16384
	ds_read_b128 v[150:153], v241 offset:17408
	ds_read_b128 v[170:173], v241 offset:18432
	ds_read_b128 v[174:177], v241 offset:19456
	s_add_u32 s16, s18, 0xffd50080
	s_addc_u32 s17, s19, -1
	s_cmpk_eq_i32 s48, 0xa8
	s_cselect_b32 s21, s5, s17
	s_cselect_b32 s20, s4, s16
	s_cselect_b32 s17, s15, s47
	s_cselect_b32 s16, s14, s46
	s_add_i32 m0, s25, 0xc000
	ds_read_b128 v[178:181], v184
	ds_read_b128 v[186:189], v184 offset:1024
	ds_read_b128 v[190:193], v184 offset:2048
	ds_read_b128 v[194:197], v184 offset:3072
	ds_read_b128 v[198:201], v184 offset:4096
	ds_read_b128 v[202:205], v184 offset:5120
	ds_read_b128 v[206:209], v184 offset:6144
	ds_read_b128 v[210:213], v184 offset:7168
	global_load_lds_dwordx4 v0, s[18:19]
	s_add_i32 m0, s25, 0xe000
	s_nop 0
	global_load_lds_dwordx4 v162, s[18:19]
	s_waitcnt vmcnt(8)
	s_waitcnt lgkmcnt(0)
	s_barrier
	s_waitcnt lgkmcnt(0)
	v_mfma_f32_16x16x32_bf16 v[114:117], v[130:133], v[178:181], v[114:117]
	v_mfma_f32_16x16x32_bf16 v[114:117], v[134:137], v[186:189], v[114:117]
	v_mfma_f32_16x16x32_bf16 v[106:109], v[134:137], v[194:197], v[106:109]
	v_mfma_f32_16x16x32_bf16 v[106:109], v[130:133], v[190:193], v[106:109]
	v_mfma_f32_16x16x32_bf16 v[90:93], v[130:133], v[198:201], v[90:93]
	v_mfma_f32_16x16x32_bf16 v[90:93], v[134:137], v[202:205], v[90:93]
	v_mfma_f32_16x16x32_bf16 v[74:77], v[134:137], v[210:213], v[74:77]
	v_mfma_f32_16x16x32_bf16 v[74:77], v[130:133], v[206:209], v[74:77]
	v_mfma_f32_16x16x32_bf16 v[66:69], v[138:141], v[206:209], v[66:69]
	v_mfma_f32_16x16x32_bf16 v[66:69], v[142:145], v[210:213], v[66:69]
	v_mfma_f32_16x16x32_bf16 v[82:85], v[142:145], v[202:205], v[82:85]
	v_mfma_f32_16x16x32_bf16 v[82:85], v[138:141], v[198:201], v[82:85]
	v_mfma_f32_16x16x32_bf16 v[98:101], v[138:141], v[190:193], v[98:101]
	v_mfma_f32_16x16x32_bf16 v[98:101], v[142:145], v[194:197], v[98:101]
	v_mfma_f32_16x16x32_bf16 v[118:121], v[142:145], v[186:189], v[118:121]
	v_mfma_f32_16x16x32_bf16 v[118:121], v[138:141], v[178:181], v[118:121]
	v_mfma_f32_16x16x32_bf16 v[122:125], v[146:149], v[178:181], v[122:125]
	v_mfma_f32_16x16x32_bf16 v[122:125], v[150:153], v[186:189], v[122:125]
	v_mfma_f32_16x16x32_bf16 v[110:113], v[150:153], v[194:197], v[110:113]
	v_mfma_f32_16x16x32_bf16 v[110:113], v[146:149], v[190:193], v[110:113]
	v_mfma_f32_16x16x32_bf16 v[94:97], v[146:149], v[198:201], v[94:97]
	v_mfma_f32_16x16x32_bf16 v[94:97], v[150:153], v[202:205], v[94:97]
	v_mfma_f32_16x16x32_bf16 v[78:81], v[150:153], v[210:213], v[78:81]
	v_mfma_f32_16x16x32_bf16 v[78:81], v[146:149], v[206:209], v[78:81]
	v_mfma_f32_16x16x32_bf16 v[70:73], v[170:173], v[206:209], v[70:73]
	v_mfma_f32_16x16x32_bf16 v[70:73], v[174:177], v[210:213], v[70:73]
	v_mfma_f32_16x16x32_bf16 v[86:89], v[174:177], v[202:205], v[86:89]
	v_mfma_f32_16x16x32_bf16 v[86:89], v[170:173], v[198:201], v[86:89]
	v_mfma_f32_16x16x32_bf16 v[102:105], v[170:173], v[190:193], v[102:105]
	v_mfma_f32_16x16x32_bf16 v[102:105], v[174:177], v[194:197], v[102:105]
	v_mfma_f32_16x16x32_bf16 v[126:129], v[174:177], v[186:189], v[126:129]
	v_mfma_f32_16x16x32_bf16 v[126:129], v[170:173], v[178:181], v[126:129]
	s_barrier
	s_add_i32 s33, s36, s24
	s_mov_b32 m0, s33
	ds_read_b128 v[178:181], v184 offset:16384
	ds_read_b128 v[186:189], v184 offset:17408
	ds_read_b128 v[190:193], v184 offset:18432
	ds_read_b128 v[194:197], v184 offset:19456
	ds_read_b128 v[198:201], v184 offset:20480
	ds_read_b128 v[202:205], v184 offset:21504
	ds_read_b128 v[206:209], v184 offset:22528
	ds_read_b128 v[210:213], v184 offset:23552
	global_load_lds_dwordx4 v156, s[16:17]
	s_add_i32 m0, s33, 0x2000
	s_add_u32 s50, s16, 0x2b0000
	s_addc_u32 s51, s17, 0
	s_add_i32 s33, s37, s24
	global_load_lds_dwordx4 v160, s[16:17]
	s_mov_b32 m0, s33
	s_add_u32 s100, s20, 0x80
	s_addc_u32 s101, s21, 0
	global_load_lds_dwordx4 v156, s[50:51]
	s_add_i32 m0, s33, 0x2000
	s_nop 0
	global_load_lds_dwordx4 v160, s[50:51]
	s_mov_b32 m0, s25
	s_nop 0
	global_load_lds_dwordx4 v154, s[20:21]
	s_mov_b32 m0, s26
	s_nop 0
	global_load_lds_dwordx4 v158, s[20:21]
	s_waitcnt vmcnt(8)
	s_waitcnt lgkmcnt(0)
	s_barrier
	s_waitcnt lgkmcnt(0)
	v_mfma_f32_16x16x32_bf16 v[58:61], v[130:133], v[178:181], v[58:61]
	v_mfma_f32_16x16x32_bf16 v[58:61], v[134:137], v[186:189], v[58:61]
	v_mfma_f32_16x16x32_bf16 v[42:45], v[134:137], v[194:197], v[42:45]
	v_mfma_f32_16x16x32_bf16 v[42:45], v[130:133], v[190:193], v[42:45]
	v_mfma_f32_16x16x32_bf16 v[26:29], v[130:133], v[198:201], v[26:29]
	v_mfma_f32_16x16x32_bf16 v[26:29], v[134:137], v[202:205], v[26:29]
	v_mfma_f32_16x16x32_bf16 v[6:9], v[134:137], v[210:213], v[6:9]
	v_mfma_f32_16x16x32_bf16 v[6:9], v[130:133], v[206:209], v[6:9]
	v_mfma_f32_16x16x32_bf16 v[2:5], v[138:141], v[206:209], v[2:5]
	v_mfma_f32_16x16x32_bf16 v[2:5], v[142:145], v[210:213], v[2:5]
	v_mfma_f32_16x16x32_bf16 v[18:21], v[142:145], v[202:205], v[18:21]
	v_mfma_f32_16x16x32_bf16 v[18:21], v[138:141], v[198:201], v[18:21]
	v_mfma_f32_16x16x32_bf16 v[34:37], v[138:141], v[190:193], v[34:37]
	v_mfma_f32_16x16x32_bf16 v[34:37], v[142:145], v[194:197], v[34:37]
	v_mfma_f32_16x16x32_bf16 v[54:57], v[142:145], v[186:189], v[54:57]
	v_mfma_f32_16x16x32_bf16 v[54:57], v[138:141], v[178:181], v[54:57]
	v_mfma_f32_16x16x32_bf16 v[62:65], v[146:149], v[178:181], v[62:65]
	v_mfma_f32_16x16x32_bf16 v[62:65], v[150:153], v[186:189], v[62:65]
	v_mfma_f32_16x16x32_bf16 v[46:49], v[150:153], v[194:197], v[46:49]
	v_mfma_f32_16x16x32_bf16 v[46:49], v[146:149], v[190:193], v[46:49]
	v_mfma_f32_16x16x32_bf16 v[30:33], v[146:149], v[198:201], v[30:33]
	v_mfma_f32_16x16x32_bf16 v[30:33], v[150:153], v[202:205], v[30:33]
	v_mfma_f32_16x16x32_bf16 v[10:13], v[150:153], v[210:213], v[10:13]
	v_mfma_f32_16x16x32_bf16 v[10:13], v[146:149], v[206:209], v[10:13]
	v_mfma_f32_16x16x32_bf16 v[14:17], v[170:173], v[206:209], v[14:17]
	v_mfma_f32_16x16x32_bf16 v[14:17], v[174:177], v[210:213], v[14:17]
	v_mfma_f32_16x16x32_bf16 v[22:25], v[174:177], v[202:205], v[22:25]
	v_mfma_f32_16x16x32_bf16 v[22:25], v[170:173], v[198:201], v[22:25]
	v_mfma_f32_16x16x32_bf16 v[38:41], v[170:173], v[190:193], v[38:41]
	v_mfma_f32_16x16x32_bf16 v[38:41], v[174:177], v[194:197], v[38:41]
	v_mfma_f32_16x16x32_bf16 v[50:53], v[174:177], v[186:189], v[50:53]
	v_mfma_f32_16x16x32_bf16 v[50:53], v[170:173], v[178:181], v[50:53]
	s_barrier
; #define PG8_STAGE(bufoff, gbase, voff) do { _Pragma("unroll") for (int _i = 0; _i < 2; ++_i) \
;         __builtin_amdgcn_global_load_lds((const unsigned*)((const char*)(gbase) + (voff)[_i]), (PG8_LAS unsigned*)(lds + (bufoff) + ldsw + _i * 8192), 16, 0, 0); } while (0)
; #define PG8_LDA(dst, b, h) do { _Pragma("unroll") for (int m = 0; m < 4; ++m) _Pragma("unroll") for (int k = 0; k < 2; ++k) dst[m][k] = *(const PG8_LAS bf16x8*)(lds + PG8_SA(b, h) + aoff + m * 2048 + k * 1024); } while (0)
; #define PG8_LDB(dst, b, h) do { _Pragma("unroll") for (int n = 0; n < 2; ++n) _Pragma("unroll") for (int k = 0; k < 2; ++k) dst[n][k] = *(const PG8_LAS bf16x8*)(lds + PG8_SB(b, h) + boff + n * 2048 + k * 1024); } while (0)
; #define PG8_MMA(ai, bj, At, Bt) do { __builtin_amdgcn_s_setprio(1); _Pragma("unroll") for (int m = 0; m < 4; ++m) _Pragma("unroll") for (int n = 0; n < 2; ++n) _Pragma("unroll") for (int k = 0; k < 2; ++k) \
;         acc[ai][bj][m][n] = __builtin_amdgcn_mfma_f32_16x16x32_bf16(Bt[n][k], At[m][k], acc[ai][bj][m][n], 0, 0, 0); __builtin_amdgcn_s_setprio(0); } while (0)
; #define PG8_WAIT_V(n) asm volatile("s_waitcnt vmcnt(" #n ")" ::: "memory")
; #define PG8_WAIT_L(n) asm volatile("s_waitcnt lgkmcnt(" #n ")" ::: "memory")
; #define PG8_BAR __builtin_amdgcn_s_barrier()
; #define PG8_SCHED __builtin_amdgcn_sched_barrier(0)
; template <class Epi, class Sched, bool ALIGN_EPI = false, bool SP2 = false>
; __device__ __forceinline__ void gemm_phase(PG8_LAS unsigned char* lds, const Gemm g, const Sched& S, const Epi& E) {
;     ...
;             PG8_LDB(B0, 1, 0); PG8_LDB(B1, 1, 1); PG8_SCHED; PG8_LDA(At, 1, 0); PG8_STAGE(PG8_SA(0, 1), a2 + hstep, voffA);
;             PG8_WAIT_V(8); PG8_WAIT_L(0); PG8_BAR; PG8_MMA(0, 0, At, B0); PG8_MMA(0, 1, At, B1); PG8_BAR; PG8_SCHED;
;             PG8_LDA(At, 1, 1); PG8_STAGE(PG8_SB(1, 0), b3, voffB); PG8_STAGE(PG8_SB(1, 1), b3 + hstep, voffB); PG8_STAGE(PG8_SA(1, 0), a3, voffA);
;             PG8_WAIT_V(8); PG8_WAIT_L(0); PG8_BAR; PG8_MMA(1, 0, At, B0); PG8_MMA(1, 1, At, B1); PG8_BAR; PG8_SCHED;
	s_add_i32 s33, 0, 0x18000
	s_add_i32 s42, 0, 0x1c000
	ds_read_b128 v[130:133], v241 offset:32768
	ds_read_b128 v[134:137], v241 offset:33792
	ds_read_b128 v[138:141], v241 offset:34816
	ds_read_b128 v[142:145], v241 offset:35840
	ds_read_b128 v[146:149], v241 offset:49152
	ds_read_b128 v[150:153], v241 offset:50176
	ds_read_b128 v[170:173], v241 offset:51200
	ds_read_b128 v[174:177], v241 offset:52224
	s_add_u32 s20, s20, 0x2b0000
	s_addc_u32 s21, s21, 0
	s_mov_b32 m0, s27
	ds_read_b128 v[178:181], v184 offset:32768
	ds_read_b128 v[186:189], v184 offset:33792
	ds_read_b128 v[190:193], v184 offset:34816
	ds_read_b128 v[194:197], v184 offset:35840
	ds_read_b128 v[198:201], v184 offset:36864
	ds_read_b128 v[202:205], v184 offset:37888
	ds_read_b128 v[206:209], v184 offset:38912
	ds_read_b128 v[210:213], v184 offset:39936
	global_load_lds_dwordx4 v154, s[20:21]
	s_mov_b32 m0, s28
	s_nop 0
	global_load_lds_dwordx4 v158, s[20:21]
	s_waitcnt vmcnt(8)
	s_waitcnt lgkmcnt(0)
	s_barrier
	s_waitcnt lgkmcnt(0)
	v_mfma_f32_16x16x32_bf16 v[114:117], v[130:133], v[178:181], v[114:117]
	v_mfma_f32_16x16x32_bf16 v[114:117], v[134:137], v[186:189], v[114:117]
	v_mfma_f32_16x16x32_bf16 v[106:109], v[134:137], v[194:197], v[106:109]
	v_mfma_f32_16x16x32_bf16 v[106:109], v[130:133], v[190:193], v[106:109]
	v_mfma_f32_16x16x32_bf16 v[90:93], v[130:133], v[198:201], v[90:93]
	v_mfma_f32_16x16x32_bf16 v[90:93], v[134:137], v[202:205], v[90:93]
	v_mfma_f32_16x16x32_bf16 v[74:77], v[134:137], v[210:213], v[74:77]
	v_mfma_f32_16x16x32_bf16 v[74:77], v[130:133], v[206:209], v[74:77]
	v_mfma_f32_16x16x32_bf16 v[66:69], v[138:141], v[206:209], v[66:69]
	v_mfma_f32_16x16x32_bf16 v[66:69], v[142:145], v[210:213], v[66:69]
	v_mfma_f32_16x16x32_bf16 v[82:85], v[142:145], v[202:205], v[82:85]
	v_mfma_f32_16x16x32_bf16 v[82:85], v[138:141], v[198:201], v[82:85]
	v_mfma_f32_16x16x32_bf16 v[98:101], v[138:141], v[190:193], v[98:101]
	v_mfma_f32_16x16x32_bf16 v[98:101], v[142:145], v[194:197], v[98:101]
	v_mfma_f32_16x16x32_bf16 v[118:121], v[142:145], v[186:189], v[118:121]
	v_mfma_f32_16x16x32_bf16 v[118:121], v[138:141], v[178:181], v[118:121]
	v_mfma_f32_16x16x32_bf16 v[122:125], v[146:149], v[178:181], v[122:125]
	v_mfma_f32_16x16x32_bf16 v[122:125], v[150:153], v[186:189], v[122:125]
	v_mfma_f32_16x16x32_bf16 v[110:113], v[150:153], v[194:197], v[110:113]
	v_mfma_f32_16x16x32_bf16 v[110:113], v[146:149], v[190:193], v[110:113]
	v_mfma_f32_16x16x32_bf16 v[94:97], v[146:149], v[198:201], v[94:97]
	v_mfma_f32_16x16x32_bf16 v[94:97], v[150:153], v[202:205], v[94:97]
	v_mfma_f32_16x16x32_bf16 v[78:81], v[150:153], v[210:213], v[78:81]
	v_mfma_f32_16x16x32_bf16 v[78:81], v[146:149], v[206:209], v[78:81]
	v_mfma_f32_16x16x32_bf16 v[70:73], v[170:173], v[206:209], v[70:73]
	v_mfma_f32_16x16x32_bf16 v[70:73], v[174:177], v[210:213], v[70:73]
	v_mfma_f32_16x16x32_bf16 v[86:89], v[174:177], v[202:205], v[86:89]
	v_mfma_f32_16x16x32_bf16 v[86:89], v[170:173], v[198:201], v[86:89]
	v_mfma_f32_16x16x32_bf16 v[102:105], v[170:173], v[190:193], v[102:105]
	v_mfma_f32_16x16x32_bf16 v[102:105], v[174:177], v[194:197], v[102:105]
	v_mfma_f32_16x16x32_bf16 v[126:129], v[174:177], v[186:189], v[126:129]
	v_mfma_f32_16x16x32_bf16 v[126:129], v[170:173], v[178:181], v[126:129]
	s_barrier
	s_add_i32 s20, s33, s24
	s_add_i32 m0, s20, 0xffffff80
	ds_read_b128 v[178:181], v184 offset:49152
	ds_read_b128 v[186:189], v184 offset:50176
	ds_read_b128 v[190:193], v184 offset:51200
	ds_read_b128 v[194:197], v184 offset:52224
	ds_read_b128 v[198:201], v184 offset:53248
	ds_read_b128 v[202:205], v184 offset:54272
	ds_read_b128 v[206:209], v184 offset:55296
	ds_read_b128 v[210:213], v184 offset:56320
	global_load_lds_dwordx4 v156, s[16:17] offset:128
	s_add_i32 m0, s20, 0x1f80
	s_add_i32 s20, s42, s24
	global_load_lds_dwordx4 v160, s[16:17] offset:128
	s_add_u32 s16, s16, 0x2b0080
	s_addc_u32 s17, s17, 0
	s_mov_b32 m0, s20
	s_nop 0
	global_load_lds_dwordx4 v156, s[16:17]
	s_add_i32 m0, s20, 0x2000
	s_nop 0
	global_load_lds_dwordx4 v160, s[16:17]
	s_mov_b32 m0, s30
	s_nop 0
	global_load_lds_dwordx4 v154, s[100:101]
	s_mov_b32 m0, s31
	s_nop 0
	global_load_lds_dwordx4 v158, s[100:101]
	s_waitcnt vmcnt(8)
	s_waitcnt lgkmcnt(0)
	s_barrier
; #define PG8_STAGE(bufoff, gbase, voff) do { _Pragma("unroll") for (int _i = 0; _i < 2; ++_i) \
;         __builtin_amdgcn_global_load_lds((const unsigned*)((const char*)(gbase) + (voff)[_i]), (PG8_LAS unsigned*)(lds + (bufoff) + ldsw + _i * 8192), 16, 0, 0); } while (0)
; #define PG8_LDA(dst, b, h) do { _Pragma("unroll") for (int m = 0; m < 4; ++m) _Pragma("unroll") for (int k = 0; k < 2; ++k) dst[m][k] = *(const PG8_LAS bf16x8*)(lds + PG8_SA(b, h) + aoff + m * 2048 + k * 1024); } while (0)
; #define PG8_MMA(ai, bj, At, Bt) do { __builtin_amdgcn_s_setprio(1); _Pragma("unroll") for (int m = 0; m < 4; ++m) _Pragma("unroll") for (int n = 0; n < 2; ++n) _Pragma("unroll") for (int k = 0; k < 2; ++k) \
;         acc[ai][bj][m][n] = __builtin_amdgcn_mfma_f32_16x16x32_bf16(Bt[n][k], At[m][k], acc[ai][bj][m][n], 0, 0, 0); __builtin_amdgcn_s_setprio(0); } while (0)
; #define PG8_WAIT_V(n) asm volatile("s_waitcnt vmcnt(" #n ")" ::: "memory")
;     __device__ __forceinline__ void operator()(const f32x4 (&acc)[2][2][4][2], const Unit& u, int wr, int wc, int fr, int fq) const {
;     ...
;                 for (int bj = 0; bj < 2; ++bj) { const size_t off = (size_t)(row0 + ai * HALF + m * 16) * ldc + col0 + bj * HALF;
;                     if (BASE_F32) { const float* bp = (const float*)base + off; b0[m][bj] = *(const f32x4*)bp; b1[m][bj] = *(const f32x4*)(bp + 4); }
;                     else { const u32x4 r = *(const u32x4*)((const bf16_t*)base + off);
;                         b0[m][bj] = (f32x4){__uint_as_float(r.x << 16), __uint_as_float(r.x & 0xffff0000u), __uint_as_float(r.y << 16), __uint_as_float(r.y & 0xffff0000u)};
;                         b1[m][bj] = (f32x4){__uint_as_float(r.z << 16), __uint_as_float(r.z & 0xffff0000u), __uint_as_float(r.w << 16), __uint_as_float(r.w & 0xffff0000u)}; } }
; template <class Epi, class Sched, bool ALIGN_EPI = false, bool SP2 = false>
; __device__ __forceinline__ void gemm_phase(PG8_LAS unsigned char* lds, const Gemm g, const Sched& S, const Epi& E) {
;     ...
;             PG8_WAIT_V(8); PG8_WAIT_L(0); PG8_BAR; PG8_MMA(0, 0, At, B0); PG8_MMA(0, 1, At, B1); PG8_BAR; PG8_SCHED;
;             PG8_LDA(At, 1, 1); PG8_STAGE(PG8_SB(1, 0), b3, voffB); PG8_STAGE(PG8_SB(1, 1), b3 + hstep, voffB); PG8_STAGE(PG8_SA(1, 0), a3, voffA);
;             PG8_WAIT_V(8); PG8_WAIT_L(0); PG8_BAR; PG8_MMA(1, 0, At, B0); PG8_MMA(1, 1, At, B1); PG8_BAR; PG8_SCHED;
	s_waitcnt lgkmcnt(0)
	v_mfma_f32_16x16x32_bf16 v[58:61], v[130:133], v[178:181], v[58:61]
	v_mfma_f32_16x16x32_bf16 v[58:61], v[134:137], v[186:189], v[58:61]
	v_mfma_f32_16x16x32_bf16 v[42:45], v[134:137], v[194:197], v[42:45]
	v_mfma_f32_16x16x32_bf16 v[42:45], v[130:133], v[190:193], v[42:45]
	v_mfma_f32_16x16x32_bf16 v[26:29], v[130:133], v[198:201], v[26:29]
	v_mfma_f32_16x16x32_bf16 v[26:29], v[134:137], v[202:205], v[26:29]
	v_mfma_f32_16x16x32_bf16 v[6:9], v[134:137], v[210:213], v[6:9]
	v_mfma_f32_16x16x32_bf16 v[6:9], v[130:133], v[206:209], v[6:9]
	v_mfma_f32_16x16x32_bf16 v[2:5], v[138:141], v[206:209], v[2:5]
	v_mfma_f32_16x16x32_bf16 v[2:5], v[142:145], v[210:213], v[2:5]
	v_mfma_f32_16x16x32_bf16 v[18:21], v[142:145], v[202:205], v[18:21]
	v_mfma_f32_16x16x32_bf16 v[18:21], v[138:141], v[198:201], v[18:21]
	v_mfma_f32_16x16x32_bf16 v[34:37], v[138:141], v[190:193], v[34:37]
	v_mfma_f32_16x16x32_bf16 v[34:37], v[142:145], v[194:197], v[34:37]
	v_mfma_f32_16x16x32_bf16 v[54:57], v[142:145], v[186:189], v[54:57]
	v_mfma_f32_16x16x32_bf16 v[54:57], v[138:141], v[178:181], v[54:57]
	v_mfma_f32_16x16x32_bf16 v[62:65], v[146:149], v[178:181], v[62:65]
	v_mfma_f32_16x16x32_bf16 v[62:65], v[150:153], v[186:189], v[62:65]
	v_mfma_f32_16x16x32_bf16 v[46:49], v[150:153], v[194:197], v[46:49]
	v_mfma_f32_16x16x32_bf16 v[46:49], v[146:149], v[190:193], v[46:49]
	v_mfma_f32_16x16x32_bf16 v[30:33], v[146:149], v[198:201], v[30:33]
	v_mfma_f32_16x16x32_bf16 v[30:33], v[150:153], v[202:205], v[30:33]
	v_mfma_f32_16x16x32_bf16 v[10:13], v[150:153], v[210:213], v[10:13]
	v_mfma_f32_16x16x32_bf16 v[10:13], v[146:149], v[206:209], v[10:13]
	v_mfma_f32_16x16x32_bf16 v[14:17], v[170:173], v[206:209], v[14:17]
	v_mfma_f32_16x16x32_bf16 v[14:17], v[174:177], v[210:213], v[14:17]
	v_mfma_f32_16x16x32_bf16 v[22:25], v[174:177], v[202:205], v[22:25]
	v_mfma_f32_16x16x32_bf16 v[22:25], v[170:173], v[198:201], v[22:25]
	v_mfma_f32_16x16x32_bf16 v[38:41], v[170:173], v[190:193], v[38:41]
	v_mfma_f32_16x16x32_bf16 v[38:41], v[174:177], v[194:197], v[38:41]
	v_mfma_f32_16x16x32_bf16 v[50:53], v[174:177], v[186:189], v[50:53]
	v_mfma_f32_16x16x32_bf16 v[50:53], v[170:173], v[178:181], v[50:53]
	s_barrier
	s_add_i32 s48, s48, 2
	s_add_u32 s18, s18, 0x100
	s_addc_u32 s19, s19, 0
	s_add_u32 s46, s46, 0x100
	s_addc_u32 s47, s47, 0
	s_cmpk_gt_u32 s48, 0xa9
	s_cbranch_scc0 .LBB0_1801
	s_and_b64 vcc, exec, s[12:13]
	s_cbranch_vccz .LBB0_1804
	v_lshl_or_b32 v170, s45, 8, v183
	v_lshl_add_u32 v174, s44, 8, v165
	v_ashrrev_i32_e32 v171, 31, v170
	v_lshlrev_b64 v[196:197], 1, v[170:171]
	v_ashrrev_i32_e32 v175, 31, v174
	v_lshl_add_u64 v[172:173], s[96:97], 0, v[196:197]
	v_lshlrev_b64 v[186:187], 13, v[174:175]
	v_lshl_add_u64 v[130:131], v[172:173], 0, v[186:187]
	global_load_dwordx4 v[188:191], v[130:131], off
	global_load_dwordx4 v[192:195], v[130:131], off offset:256
	v_or_b32_e32 v180, 16, v174
	v_or_b32_e32 v178, 32, v174
	v_or_b32_e32 v176, 48, v174
	v_ashrrev_i32_e32 v181, 31, v180
	v_ashrrev_i32_e32 v179, 31, v178
	v_ashrrev_i32_e32 v177, 31, v176
	v_lshlrev_b64 v[130:131], 13, v[180:181]
	v_lshlrev_b64 v[132:133], 13, v[178:179]
	v_lshlrev_b64 v[134:135], 13, v[176:177]
	v_lshl_add_u64 v[130:131], v[172:173], 0, v[130:131]
	v_lshl_add_u64 v[132:133], v[172:173], 0, v[132:133]
	v_lshl_add_u64 v[198:199], v[172:173], 0, v[134:135]
	global_load_dwordx4 v[150:153], v[130:131], off
	global_load_dwordx4 v[146:149], v[130:131], off offset:256
	global_load_dwordx4 v[142:145], v[132:133], off
	global_load_dwordx4 v[138:141], v[132:133], off offset:256
	global_load_dwordx4 v[134:137], v[198:199], off
	s_nop 0
	global_load_dwordx4 v[130:133], v[198:199], off offset:256
	s_barrier
	s_branch .Lepi_rest_1804

; __device__ __forceinline__ unsigned cvt_pk_bf16(float lo, float hi) { unsigned r; asm volatile("v_cvt_pk_bf16_f32 %0, %1, %2" : "=v"(r) : "v"(lo), "v"(hi)); return r; }
; __device__ __forceinline__ unsigned cvt_pk_bf16(float lo, float hi) { unsigned r; asm volatile("v_cvt_pk_bf16_f32 %0, %1, %2" : "=v"(r) : "v"(lo), "v"(hi)); return r; }
;     __device__ __forceinline__ void operator()(const f32x4 (&acc)[2][2][4][2], const Unit& u, int wr, int wc, int fr, int fq) const {
;     ...
;                     else { const u32x4 r = *(const u32x4*)((const bf16_t*)base + off);
;                         b0[m][bj] = (f32x4){__uint_as_float(r.x << 16), __uint_as_float(r.x & 0xffff0000u), __uint_as_float(r.y << 16), __uint_as_float(r.y & 0xffff0000u)};
;                         b1[m][bj] = (f32x4){__uint_as_float(r.z << 16), __uint_as_float(r.z & 0xffff0000u), __uint_as_float(r.w << 16), __uint_as_float(r.w & 0xffff0000u)}; } }
; #pragma unroll
;             for (int m = 0; m < 4; ++m) { const int row = row0 + ai * HALF + m * 16; const size_t off = (size_t)row * ldc + col0; f32x2 q2 = {0.f, 0.f};
; #pragma unroll
;                 for (int bj = 0; bj < 2; ++bj) { const f32x4 v0 = acc[ai][bj][m][0] + b0[m][bj], v1 = acc[ai][bj][m][1] + b1[m][bj];
;                     { const f32x2 e0 = {v0[0], v0[1]}, e1 = {v0[2], v0[3]}, e2 = {v1[0], v1[1]}, e3 = {v1[2], v1[3]}; q2 = e0 * e0 + q2; q2 = e1 * e1 + q2; q2 = e2 * e2 + q2; q2 = e3 * e3 + q2; }
;                     u32x4 w; w.x = cvt_pk_bf16(v0[0], v0[1]); w.y = cvt_pk_bf16(v0[2], v0[3]); w.z = cvt_pk_bf16(v1[0], v1[1]); w.w = cvt_pk_bf16(v1[2], v1[3]);
;                     *(u32x4*)(out + off + bj * HALF) = w; }
;                 float q = q2.x + q2.y; q += __shfl_xor(q, 16); q += __shfl_xor(q, 32);
;                 if (fq == 0) atomicAdd(ssq + row, (ssq_t)(q * SSQ_FIX + 0.5f)); }
.Lepi_rest_1804:
	v_and_b32_e32 v199, 64, v185
	v_xor_b32_e32 v198, 16, v185
	v_add_u32_e32 v199, 64, v199
	v_xor_b32_e32 v200, 32, v185
	v_cmp_lt_i32_e32 vcc, v198, v199
	s_waitcnt vmcnt(0)
	v_lshlrev_b32_e32 v202, 16, v192
	v_cndmask_b32_e32 v201, v185, v198, vcc
	v_cmp_lt_i32_e32 vcc, v200, v199
	v_lshl_add_u64 v[198:199], s[96:97], 0, v[186:187]
	v_lshl_add_u64 v[196:197], v[198:199], 0, v[196:197]
	v_lshlrev_b32_e32 v198, 16, v188
	v_and_b32_e32 v199, 0xffff0000, v188
	v_lshlrev_b32_e32 v188, 16, v189
	v_and_b32_e32 v189, 0xffff0000, v189
	v_cndmask_b32_e32 v206, v185, v200, vcc
	v_lshlrev_b32_e32 v186, 2, v201
	v_lshlrev_b32_e32 v200, 16, v190
	v_and_b32_e32 v201, 0xffff0000, v190
	v_lshlrev_b32_e32 v190, 16, v191
	v_and_b32_e32 v191, 0xffff0000, v191
	v_pk_add_f32 v[116:117], v[116:117], v[188:189]
	v_pk_add_f32 v[188:189], v[114:115], v[198:199]
	v_pk_add_f32 v[120:121], v[120:121], v[190:191]
	v_pk_mul_f32 v[190:191], v[116:117], v[116:117]
	v_pk_add_f32 v[118:119], v[118:119], v[200:201]
	v_cvt_pk_bf16_f32 v114, v188, v189
	v_cvt_pk_bf16_f32 v115, v116, v117
	v_pk_fma_f32 v[116:117], v[188:189], v[188:189], v[190:191]
	v_and_b32_e32 v203, 0xffff0000, v192
	v_pk_fma_f32 v[116:117], v[118:119], v[118:119], v[116:117]
	v_lshlrev_b32_e32 v192, 16, v193
	v_and_b32_e32 v193, 0xffff0000, v193
	v_pk_add_f32 v[122:123], v[122:123], v[202:203]
	v_pk_fma_f32 v[116:117], v[120:121], v[120:121], v[116:117]
	v_lshlrev_b32_e32 v204, 16, v194
	v_and_b32_e32 v205, 0xffff0000, v194
	v_pk_add_f32 v[124:125], v[124:125], v[192:193]
	v_pk_fma_f32 v[116:117], v[122:123], v[122:123], v[116:117]
	v_lshlrev_b32_e32 v194, 16, v195
	v_and_b32_e32 v195, 0xffff0000, v195
	v_pk_add_f32 v[126:127], v[126:127], v[204:205]
	v_pk_fma_f32 v[116:117], v[124:125], v[124:125], v[116:117]
	v_pk_add_f32 v[128:129], v[128:129], v[194:195]
	v_pk_fma_f32 v[116:117], v[126:127], v[126:127], v[116:117]
	s_nop 0
	v_pk_fma_f32 v[116:117], v[128:129], v[128:129], v[116:117]
	s_nop 0
	v_add_f32_e32 v187, v116, v117
	ds_bpermute_b32 v188, v186, v187
	v_cvt_pk_bf16_f32 v116, v118, v119
	v_cvt_pk_bf16_f32 v117, v120, v121
	global_store_dwordx4 v[196:197], v[114:117], off
	v_cvt_pk_bf16_f32 v118, v122, v123
	v_cvt_pk_bf16_f32 v119, v124, v125
	v_cvt_pk_bf16_f32 v120, v126, v127
	v_cvt_pk_bf16_f32 v121, v128, v129
	global_store_dwordx4 v[196:197], v[118:121], off offset:256
	s_waitcnt lgkmcnt(0)
	v_add_f32_e32 v115, v187, v188
	v_lshlrev_b32_e32 v114, 2, v206
	ds_bpermute_b32 v116, v114, v115
	s_and_saveexec_b64 s[16:17], s[0:1]
	s_cbranch_execz .LBB0_1806
	s_waitcnt lgkmcnt(0)
	v_add_f32_e32 v115, v115, v116
	v_fma_f32 v115, v115, s40, 0.5
	v_trunc_f32_e32 v115, v115
	v_mul_f32_e32 v116, 0x2f800000, v115
	v_floor_f32_e32 v117, v116
	v_fmac_f32_e32 v115, 0xcf800000, v117
	v_cvt_u32_f32_e32 v116, v115
	v_cvt_u32_f32_e32 v117, v117
	v_lshl_add_u64 v[118:119], v[174:175], 3, s[8:9]
	global_atomic_add_x2 v[118:119], v[116:117], off
